# K-loop load segments now VALU-free: B-fragment LDS read addresses precomputed per tile (4 VALU/iteration removed), on top of no-setprio + SGPR-base DMA + lean in-proj epilogue
# baseline (speedup 1.0000x reference)
; #define PG8_STAGE(bufoff, gbase, voff) do { _Pragma("unroll") for (int _i = 0; _i < 2; ++_i) \
;         __builtin_amdgcn_global_load_lds((const unsigned*)((const char*)(gbase) + (voff)[_i]), (PG8_LAS unsigned*)(lds + (bufoff) + ldsw + _i * 8192), 16, 0, 0); } while (0)
; #define PG8_LDA(dst, b, h) do { _Pragma("unroll") for (int m = 0; m < 4; ++m) _Pragma("unroll") for (int k = 0; k < 2; ++k) dst[m][k] = *(const PG8_LAS bf16x8*)(lds + PG8_SA(b, h) + aoff + m * 2048 + k * 1024); } while (0)
; #define PG8_LDB(dst, b, h) do { _Pragma("unroll") for (int n = 0; n < 2; ++n) _Pragma("unroll") for (int k = 0; k < 2; ++k) dst[n][k] = *(const PG8_LAS bf16x8*)(lds + PG8_SB(b, h) + boff + n * 2048 + k * 1024); } while (0)
; #define PG8_SCHED __builtin_amdgcn_sched_barrier(0)
; template <class Epi, class Sched, bool ALIGN_EPI = false, bool SP2 = false>
; __device__ __forceinline__ void gemm_phase(PG8_LAS unsigned char* lds, const Gemm g, const Sched& S, const Epi& E) {
;     ...
;         const bool has_next = S.next(ui + 1, nxt);
;         const char* nA = has_next ? (const char*)g.A + (size_t)nxt.pm * tstepA : cA; const char* nB = has_next ? (const char*)g.Bt + (size_t)nxt.pn * tstepB : cB;
;         for (int t = 0; t < nt; t += 2) {
;             const bool last = (t == nt - 2);
;             const char* a1 = cA + (size_t)(t + 1) * kstep;
;             const char* a2 = last ? nA : cA + (size_t)(t + 2) * kstep; const char* b2 = last ? nB : cB + (size_t)(t + 2) * kstep;
;             const char* a3 = a2 + kstep; const char* b3 = b2 + kstep;
;             if (last && has_next) S.a_ready(nxt);
;             if constexpr (SP2) {
;             PG8_LDB(B0, 0, 0); PG8_LDB(B1, 0, 1); PG8_SCHED; PG8_LDA(At, 0, 0); PG8_STAGE(PG8_SA(1, 1), a1 + hstepA, voffA);
;     ...
; #pragma unroll
;         for (int a = 0; a < 2; ++a)
; #pragma unroll
;             for (int b = 0; b < 2; ++b)
; #pragma unroll
;                 for (int m = 0; m < 4; ++m)
; #pragma unroll
;                     for (int n = 0; n < 2; ++n) acc[a][b][m][n] = (f32x4){0.f, 0.f, 0.f, 0.f};
;         cur = nxt; cA = nA; cB = nB; ++ui;
.LBB0_633:
	s_ashr_i32 s17, s16, 31
	s_lshl_b64 s[2:3], s[16:17], 19
	s_add_u32 s66, s58, s2
	s_addc_u32 s67, s59, s3
	s_and_b64 s[2:3], s[4:5], exec
	s_cselect_b32 s17, s67, s1
	s_cselect_b32 s78, s66, s0
	s_ashr_i32 s15, s14, 31
	s_lshl_b64 s[2:3], s[14:15], 19
	v_readlane_b32 s15, v254, 12
	s_add_u32 s82, s15, s2
	v_readlane_b32 s2, v254, 14
	s_addc_u32 s83, s2, s3
	s_and_b64 s[2:3], s[4:5], exec
	s_cselect_b32 s15, s83, s7
	s_cselect_b32 s87, s82, s6
	s_add_u32 s93, s6, 0x100
	s_addc_u32 s94, s7, 0
	s_add_u32 s0, s0, 0x40080
	v_mov_b32_e32 v0, 0
	s_addc_u32 s1, s1, 0
	s_mov_b32 s95, -2
	v_mov_b32_e32 v1, v0
	v_mov_b32_e32 v2, v0
	v_mov_b32_e32 v3, v0
	v_mov_b32_e32 v4, v0
	v_mov_b32_e32 v5, v0
	v_mov_b32_e32 v6, v0
	v_mov_b32_e32 v7, v0
	v_mov_b32_e32 v16, v0
	v_mov_b32_e32 v17, v0
	v_mov_b32_e32 v18, v0
	v_mov_b32_e32 v19, v0
	v_mov_b32_e32 v20, v0
	v_mov_b32_e32 v21, v0
	v_mov_b32_e32 v22, v0
	v_mov_b32_e32 v23, v0
	v_mov_b32_e32 v32, v0
	v_mov_b32_e32 v33, v0
	v_mov_b32_e32 v34, v0
	v_mov_b32_e32 v35, v0
	v_mov_b32_e32 v36, v0
	v_mov_b32_e32 v37, v0
	v_mov_b32_e32 v38, v0
	v_mov_b32_e32 v39, v0
	v_mov_b32_e32 v48, v0
	v_mov_b32_e32 v49, v0
	v_mov_b32_e32 v50, v0
	v_mov_b32_e32 v51, v0
	v_mov_b32_e32 v52, v0
	v_mov_b32_e32 v53, v0
	v_mov_b32_e32 v54, v0
	v_mov_b32_e32 v55, v0
	v_mov_b32_e32 v8, v0
	v_mov_b32_e32 v9, v0
	v_mov_b32_e32 v10, v0
	v_mov_b32_e32 v11, v0
	v_mov_b32_e32 v12, v0
	v_mov_b32_e32 v13, v0
	v_mov_b32_e32 v14, v0
	v_mov_b32_e32 v15, v0
	v_mov_b32_e32 v24, v0
	v_mov_b32_e32 v25, v0
	v_mov_b32_e32 v26, v0
	v_mov_b32_e32 v27, v0
	v_mov_b32_e32 v28, v0
	v_mov_b32_e32 v29, v0
	v_mov_b32_e32 v30, v0
	v_mov_b32_e32 v31, v0
	v_mov_b32_e32 v40, v0
	v_mov_b32_e32 v41, v0
	v_mov_b32_e32 v42, v0
	v_mov_b32_e32 v43, v0
	v_mov_b32_e32 v44, v0
	v_mov_b32_e32 v45, v0
	v_mov_b32_e32 v46, v0
	v_mov_b32_e32 v47, v0
	v_mov_b32_e32 v56, v0
	v_mov_b32_e32 v57, v0
	v_mov_b32_e32 v58, v0
	v_mov_b32_e32 v59, v0
	v_mov_b32_e32 v60, v0
	v_mov_b32_e32 v61, v0
	v_mov_b32_e32 v62, v0
	v_mov_b32_e32 v63, v0
	s_waitcnt vmcnt(0)
	v_mov_b32_e32 v64, v0
	v_mov_b32_e32 v65, v0
	v_mov_b32_e32 v66, v0
	v_mov_b32_e32 v67, v0
	v_mov_b32_e32 v68, v0
	v_mov_b32_e32 v69, v0
	v_mov_b32_e32 v70, v0
	v_mov_b32_e32 v71, v0
	v_mov_b32_e32 v80, v0
	v_mov_b32_e32 v81, v0
	v_mov_b32_e32 v82, v0
	v_mov_b32_e32 v83, v0
	v_mov_b32_e32 v84, v0
	v_mov_b32_e32 v85, v0
	v_mov_b32_e32 v86, v0
	v_mov_b32_e32 v87, v0
	v_mov_b32_e32 v96, v0
	v_mov_b32_e32 v97, v0
	v_mov_b32_e32 v98, v0
	v_mov_b32_e32 v99, v0
	v_mov_b32_e32 v100, v0
	v_mov_b32_e32 v101, v0
	v_mov_b32_e32 v102, v0
	v_mov_b32_e32 v103, v0
	v_mov_b32_e32 v116, v0
	v_mov_b32_e32 v117, v0
	v_mov_b32_e32 v118, v0
	v_mov_b32_e32 v119, v0
	v_mov_b32_e32 v124, v0
	v_mov_b32_e32 v125, v0
	v_mov_b32_e32 v126, v0
	v_mov_b32_e32 v127, v0
	v_mov_b32_e32 v72, v0
	v_mov_b32_e32 v73, v0
	v_mov_b32_e32 v74, v0
	v_mov_b32_e32 v75, v0
	v_mov_b32_e32 v76, v0
	v_mov_b32_e32 v77, v0
	v_mov_b32_e32 v78, v0
	v_mov_b32_e32 v79, v0
	v_mov_b32_e32 v88, v0
	v_mov_b32_e32 v89, v0
	v_mov_b32_e32 v90, v0
	v_mov_b32_e32 v91, v0
	v_mov_b32_e32 v92, v0
	v_mov_b32_e32 v93, v0
	v_mov_b32_e32 v94, v0
	v_mov_b32_e32 v95, v0
	v_mov_b32_e32 v104, v0
	v_mov_b32_e32 v105, v0
	v_mov_b32_e32 v106, v0
	v_mov_b32_e32 v107, v0
	v_mov_b32_e32 v108, v0
	v_mov_b32_e32 v109, v0
	v_mov_b32_e32 v110, v0
	v_mov_b32_e32 v111, v0
	v_mov_b32_e32 v132, v0
	v_mov_b32_e32 v133, v0
	v_mov_b32_e32 v134, v0
	v_mov_b32_e32 v135, v0
	v_mov_b32_e32 v136, v0
	v_mov_b32_e32 v137, v0
	v_mov_b32_e32 v138, v0
	v_mov_b32_e32 v139, v0
	v_add_u32_e32 v214, 0x10000, v230
	v_add_u32_e32 v215, 0x14000, v230
	v_add_u32_e32 v216, 0x18000, v230
	v_add_u32_e32 v217, 0x1c000, v230
.LBB0_634:
	s_add_u32 s2, s0, 0xfffc0080
	s_addc_u32 s3, s1, -1
	s_add_i32 s30, 0, 0x10000
	s_cmp_eq_u32 s95, 12
	s_cselect_b32 s85, s17, s3
	s_cselect_b32 s84, s78, s2
	s_cselect_b32 s7, s15, s94
	s_cselect_b32 s6, s87, s93
	s_add_i32 s31, 0, 0x14000
	ds_read_b128 v[112:115], v214
	ds_read_b128 v[120:123], v214 offset:1024
	ds_read_b128 v[128:131], v214 offset:2048
	ds_read_b128 v[140:143], v214 offset:3072
	ds_read_b128 v[144:147], v215
	ds_read_b128 v[148:151], v215 offset:1024
	ds_read_b128 v[152:155], v215 offset:2048
	ds_read_b128 v[156:159], v215 offset:3072
	s_add_i32 m0, s20, 0xc000
	ds_read_b128 v[160:163], v231
	ds_read_b128 v[164:167], v231 offset:1024
	ds_read_b128 v[168:171], v231 offset:2048
	ds_read_b128 v[172:175], v231 offset:3072
	ds_read_b128 v[186:189], v231 offset:4096
	ds_read_b128 v[198:201], v231 offset:5120
	ds_read_b128 v[202:205], v231 offset:6144
	ds_read_b128 v[206:209], v231 offset:7168
	global_load_lds_dwordx4 v184, s[0:1]
	s_add_i32 m0, s20, 0xe000
	s_nop 0
	global_load_lds_dwordx4 v182, s[0:1]
	s_waitcnt vmcnt(8)
	s_waitcnt lgkmcnt(0)
	s_barrier
; #define PG8_STAGE(bufoff, gbase, voff) do { _Pragma("unroll") for (int _i = 0; _i < 2; ++_i) \
;         __builtin_amdgcn_global_load_lds((const unsigned*)((const char*)(gbase) + (voff)[_i]), (PG8_LAS unsigned*)(lds + (bufoff) + ldsw + _i * 8192), 16, 0, 0); } while (0)
; #define PG8_LDA(dst, b, h) do { _Pragma("unroll") for (int m = 0; m < 4; ++m) _Pragma("unroll") for (int k = 0; k < 2; ++k) dst[m][k] = *(const PG8_LAS bf16x8*)(lds + PG8_SA(b, h) + aoff + m * 2048 + k * 1024); } while (0)
; #define PG8_LDB(dst, b, h) do { _Pragma("unroll") for (int n = 0; n < 2; ++n) _Pragma("unroll") for (int k = 0; k < 2; ++k) dst[n][k] = *(const PG8_LAS bf16x8*)(lds + PG8_SB(b, h) + boff + n * 2048 + k * 1024); } while (0)
; #define PG8_MMA(ai, bj, At, Bt) do { __builtin_amdgcn_s_setprio(1); _Pragma("unroll") for (int m = 0; m < 4; ++m) _Pragma("unroll") for (int n = 0; n < 2; ++n) _Pragma("unroll") for (int k = 0; k < 2; ++k) \
;         acc[ai][bj][m][n] = __builtin_amdgcn_mfma_f32_16x16x32_bf16(Bt[n][k], At[m][k], acc[ai][bj][m][n], 0, 0, 0); __builtin_amdgcn_s_setprio(0); } while (0)
; #define PG8_WAIT_V(n) asm volatile("s_waitcnt vmcnt(" #n ")" ::: "memory")
; #define PG8_WAIT_L(n) asm volatile("s_waitcnt lgkmcnt(" #n ")" ::: "memory")
; #define PG8_BAR __builtin_amdgcn_s_barrier()
; #define PG8_SCHED __builtin_amdgcn_sched_barrier(0)
; template <class Epi, class Sched, bool ALIGN_EPI = false, bool SP2 = false>
; __device__ __forceinline__ void gemm_phase(PG8_LAS unsigned char* lds, const Gemm g, const Sched& S, const Epi& E) {
;     ...
;             PG8_LDB(B0, 0, 0); PG8_LDB(B1, 0, 1); PG8_SCHED; PG8_LDA(At, 0, 0); PG8_STAGE(PG8_SA(1, 1), a1 + hstepA, voffA);
;             PG8_WAIT_V(8); PG8_WAIT_L(0); PG8_BAR; PG8_MMA(0, 0, At, B0); PG8_MMA(0, 1, At, B1); PG8_BAR; PG8_SCHED;
;             PG8_LDA(At, 0, 1); PG8_STAGE(PG8_SB(0, 0), b2, voffB); PG8_STAGE(PG8_SB(0, 1), b2 + hstepB, voffB); PG8_STAGE(PG8_SA(0, 0), a2, voffA);
;             PG8_WAIT_V(8); PG8_WAIT_L(0); PG8_BAR; PG8_MMA(1, 0, At, B0); PG8_MMA(1, 1, At, B1); PG8_BAR; PG8_SCHED;
	s_waitcnt lgkmcnt(0)
	v_mfma_f32_16x16x32_bf16 v[136:139], v[112:115], v[160:163], v[136:139]
	v_mfma_f32_16x16x32_bf16 v[132:135], v[128:131], v[160:163], v[132:135]
	v_mfma_f32_16x16x32_bf16 v[108:111], v[112:115], v[168:171], v[108:111]
	v_mfma_f32_16x16x32_bf16 v[104:107], v[128:131], v[168:171], v[104:107]
	v_mfma_f32_16x16x32_bf16 v[92:95], v[112:115], v[186:189], v[92:95]
	v_mfma_f32_16x16x32_bf16 v[88:91], v[128:131], v[186:189], v[88:91]
	v_mfma_f32_16x16x32_bf16 v[76:79], v[112:115], v[202:205], v[76:79]
	v_mfma_f32_16x16x32_bf16 v[72:75], v[128:131], v[202:205], v[72:75]
	v_mfma_f32_16x16x32_bf16 v[136:139], v[120:123], v[164:167], v[136:139]
	v_mfma_f32_16x16x32_bf16 v[132:135], v[140:143], v[164:167], v[132:135]
	v_mfma_f32_16x16x32_bf16 v[108:111], v[120:123], v[172:175], v[108:111]
	v_mfma_f32_16x16x32_bf16 v[104:107], v[140:143], v[172:175], v[104:107]
	v_mfma_f32_16x16x32_bf16 v[92:95], v[120:123], v[198:201], v[92:95]
	v_mfma_f32_16x16x32_bf16 v[88:91], v[140:143], v[198:201], v[88:91]
	v_mfma_f32_16x16x32_bf16 v[76:79], v[120:123], v[206:209], v[76:79]
	v_mfma_f32_16x16x32_bf16 v[72:75], v[140:143], v[206:209], v[72:75]
	v_mfma_f32_16x16x32_bf16 v[124:127], v[144:147], v[160:163], v[124:127]
	v_mfma_f32_16x16x32_bf16 v[116:119], v[152:155], v[160:163], v[116:119]
	v_mfma_f32_16x16x32_bf16 v[100:103], v[144:147], v[168:171], v[100:103]
	v_mfma_f32_16x16x32_bf16 v[96:99], v[152:155], v[168:171], v[96:99]
	v_mfma_f32_16x16x32_bf16 v[84:87], v[144:147], v[186:189], v[84:87]
	v_mfma_f32_16x16x32_bf16 v[80:83], v[152:155], v[186:189], v[80:83]
	v_mfma_f32_16x16x32_bf16 v[68:71], v[144:147], v[202:205], v[68:71]
	v_mfma_f32_16x16x32_bf16 v[64:67], v[152:155], v[202:205], v[64:67]
	v_mfma_f32_16x16x32_bf16 v[124:127], v[148:151], v[164:167], v[124:127]
	v_mfma_f32_16x16x32_bf16 v[116:119], v[156:159], v[164:167], v[116:119]
	v_mfma_f32_16x16x32_bf16 v[100:103], v[148:151], v[172:175], v[100:103]
	v_mfma_f32_16x16x32_bf16 v[96:99], v[156:159], v[172:175], v[96:99]
	v_mfma_f32_16x16x32_bf16 v[84:87], v[148:151], v[198:201], v[84:87]
	v_mfma_f32_16x16x32_bf16 v[80:83], v[156:159], v[198:201], v[80:83]
	v_mfma_f32_16x16x32_bf16 v[68:71], v[148:151], v[206:209], v[68:71]
	v_mfma_f32_16x16x32_bf16 v[64:67], v[156:159], v[206:209], v[64:67]
	s_barrier
	s_add_i32 s2, s30, s19
	s_mov_b32 m0, s2
	ds_read_b128 v[160:163], v231 offset:16384
	ds_read_b128 v[164:167], v231 offset:17408
	ds_read_b128 v[168:171], v231 offset:18432
	ds_read_b128 v[172:175], v231 offset:19456
	ds_read_b128 v[186:189], v231 offset:20480
	ds_read_b128 v[198:201], v231 offset:21504
	ds_read_b128 v[202:205], v231 offset:22528
	ds_read_b128 v[206:209], v231 offset:23552
	global_load_lds_dwordx4 v192, s[6:7]
	s_add_i32 m0, s2, 0x2000
	s_add_u32 s2, s6, 0x40000
	s_addc_u32 s3, s7, 0
	s_add_i32 s30, s31, s19
	global_load_lds_dwordx4 v176, s[6:7]
	s_mov_b32 m0, s30
	s_nop 0
	global_load_lds_dwordx4 v192, s[2:3]
	s_add_i32 m0, s30, 0x2000
	s_nop 0
	global_load_lds_dwordx4 v176, s[2:3]
	s_mov_b32 m0, s20
	s_nop 0
	global_load_lds_dwordx4 v180, s[84:85]
	s_mov_b32 m0, s21
	s_nop 0
	global_load_lds_dwordx4 v178, s[84:85]
	s_waitcnt vmcnt(8)
	s_waitcnt lgkmcnt(0)
	s_barrier
	s_waitcnt lgkmcnt(0)
	v_mfma_f32_16x16x32_bf16 v[60:63], v[112:115], v[160:163], v[60:63]
	v_mfma_f32_16x16x32_bf16 v[56:59], v[128:131], v[160:163], v[56:59]
	v_mfma_f32_16x16x32_bf16 v[44:47], v[112:115], v[168:171], v[44:47]
	v_mfma_f32_16x16x32_bf16 v[40:43], v[128:131], v[168:171], v[40:43]
	v_mfma_f32_16x16x32_bf16 v[28:31], v[112:115], v[186:189], v[28:31]
	v_mfma_f32_16x16x32_bf16 v[24:27], v[128:131], v[186:189], v[24:27]
	v_mfma_f32_16x16x32_bf16 v[12:15], v[112:115], v[202:205], v[12:15]
	v_mfma_f32_16x16x32_bf16 v[8:11], v[128:131], v[202:205], v[8:11]
	v_mfma_f32_16x16x32_bf16 v[60:63], v[120:123], v[164:167], v[60:63]
	v_mfma_f32_16x16x32_bf16 v[56:59], v[140:143], v[164:167], v[56:59]
	v_mfma_f32_16x16x32_bf16 v[44:47], v[120:123], v[172:175], v[44:47]
	v_mfma_f32_16x16x32_bf16 v[40:43], v[140:143], v[172:175], v[40:43]
	v_mfma_f32_16x16x32_bf16 v[28:31], v[120:123], v[198:201], v[28:31]
	v_mfma_f32_16x16x32_bf16 v[24:27], v[140:143], v[198:201], v[24:27]
	v_mfma_f32_16x16x32_bf16 v[12:15], v[120:123], v[206:209], v[12:15]
	v_mfma_f32_16x16x32_bf16 v[8:11], v[140:143], v[206:209], v[8:11]
	v_mfma_f32_16x16x32_bf16 v[52:55], v[144:147], v[160:163], v[52:55]
	v_mfma_f32_16x16x32_bf16 v[48:51], v[152:155], v[160:163], v[48:51]
	v_mfma_f32_16x16x32_bf16 v[36:39], v[144:147], v[168:171], v[36:39]
	v_mfma_f32_16x16x32_bf16 v[32:35], v[152:155], v[168:171], v[32:35]
	v_mfma_f32_16x16x32_bf16 v[20:23], v[144:147], v[186:189], v[20:23]
	v_mfma_f32_16x16x32_bf16 v[16:19], v[152:155], v[186:189], v[16:19]
	v_mfma_f32_16x16x32_bf16 v[4:7], v[144:147], v[202:205], v[4:7]
	v_mfma_f32_16x16x32_bf16 v[0:3], v[152:155], v[202:205], v[0:3]
	v_mfma_f32_16x16x32_bf16 v[52:55], v[148:151], v[164:167], v[52:55]
	v_mfma_f32_16x16x32_bf16 v[48:51], v[156:159], v[164:167], v[48:51]
	v_mfma_f32_16x16x32_bf16 v[36:39], v[148:151], v[172:175], v[36:39]
	v_mfma_f32_16x16x32_bf16 v[32:35], v[156:159], v[172:175], v[32:35]
	v_mfma_f32_16x16x32_bf16 v[20:23], v[148:151], v[198:201], v[20:23]
	v_mfma_f32_16x16x32_bf16 v[16:19], v[156:159], v[198:201], v[16:19]
	v_mfma_f32_16x16x32_bf16 v[4:7], v[148:151], v[206:209], v[4:7]
	v_mfma_f32_16x16x32_bf16 v[0:3], v[156:159], v[206:209], v[0:3]
	s_barrier
; #define PG8_STAGE(bufoff, gbase, voff) do { _Pragma("unroll") for (int _i = 0; _i < 2; ++_i) \
;         __builtin_amdgcn_global_load_lds((const unsigned*)((const char*)(gbase) + (voff)[_i]), (PG8_LAS unsigned*)(lds + (bufoff) + ldsw + _i * 8192), 16, 0, 0); } while (0)
; #define PG8_LDA(dst, b, h) do { _Pragma("unroll") for (int m = 0; m < 4; ++m) _Pragma("unroll") for (int k = 0; k < 2; ++k) dst[m][k] = *(const PG8_LAS bf16x8*)(lds + PG8_SA(b, h) + aoff + m * 2048 + k * 1024); } while (0)
; #define PG8_LDB(dst, b, h) do { _Pragma("unroll") for (int n = 0; n < 2; ++n) _Pragma("unroll") for (int k = 0; k < 2; ++k) dst[n][k] = *(const PG8_LAS bf16x8*)(lds + PG8_SB(b, h) + boff + n * 2048 + k * 1024); } while (0)
; #define PG8_MMA(ai, bj, At, Bt) do { __builtin_amdgcn_s_setprio(1); _Pragma("unroll") for (int m = 0; m < 4; ++m) _Pragma("unroll") for (int n = 0; n < 2; ++n) _Pragma("unroll") for (int k = 0; k < 2; ++k) \
;         acc[ai][bj][m][n] = __builtin_amdgcn_mfma_f32_16x16x32_bf16(Bt[n][k], At[m][k], acc[ai][bj][m][n], 0, 0, 0); __builtin_amdgcn_s_setprio(0); } while (0)
; #define PG8_WAIT_V(n) asm volatile("s_waitcnt vmcnt(" #n ")" ::: "memory")
; #define PG8_WAIT_L(n) asm volatile("s_waitcnt lgkmcnt(" #n ")" ::: "memory")
; #define PG8_BAR __builtin_amdgcn_s_barrier()
; #define PG8_SCHED __builtin_amdgcn_sched_barrier(0)
; template <class Epi, class Sched, bool ALIGN_EPI = false, bool SP2 = false>
; __device__ __forceinline__ void gemm_phase(PG8_LAS unsigned char* lds, const Gemm g, const Sched& S, const Epi& E) {
;     ...
;             PG8_LDB(B0, 1, 0); PG8_LDB(B1, 1, 1); PG8_SCHED; PG8_LDA(At, 1, 0); PG8_STAGE(PG8_SA(0, 1), a2 + hstepA, voffA);
;             PG8_WAIT_V(8); PG8_WAIT_L(0); PG8_BAR; PG8_MMA(0, 0, At, B0); PG8_MMA(0, 1, At, B1); PG8_BAR; PG8_SCHED;
;             PG8_LDA(At, 1, 1); PG8_STAGE(PG8_SB(1, 0), b3, voffB); PG8_STAGE(PG8_SB(1, 1), b3 + hstepB, voffB); PG8_STAGE(PG8_SA(1, 0), a3, voffA);
;             PG8_WAIT_V(8); PG8_WAIT_L(0); PG8_BAR; PG8_MMA(1, 0, At, B0); PG8_MMA(1, 1, At, B1); PG8_BAR; PG8_SCHED;
	s_add_i32 s30, 0, 0x18000
	s_add_i32 s31, 0, 0x1c000
	ds_read_b128 v[112:115], v216
	ds_read_b128 v[120:123], v216 offset:1024
	ds_read_b128 v[128:131], v216 offset:2048
	ds_read_b128 v[140:143], v216 offset:3072
	ds_read_b128 v[144:147], v217
	ds_read_b128 v[148:151], v217 offset:1024
	ds_read_b128 v[152:155], v217 offset:2048
	ds_read_b128 v[156:159], v217 offset:3072
	s_add_u32 s2, s84, 0x40000
	s_addc_u32 s3, s85, 0
	s_mov_b32 m0, s45
	ds_read_b128 v[160:163], v231 offset:32768
	ds_read_b128 v[164:167], v231 offset:33792
	ds_read_b128 v[168:171], v231 offset:34816
	ds_read_b128 v[172:175], v231 offset:35840
	ds_read_b128 v[186:189], v231 offset:36864
	ds_read_b128 v[198:201], v231 offset:37888
	ds_read_b128 v[202:205], v231 offset:38912
	ds_read_b128 v[206:209], v231 offset:39936
	global_load_lds_dwordx4 v180, s[2:3]
	s_mov_b32 m0, s49
	s_nop 0
	global_load_lds_dwordx4 v178, s[2:3]
	s_waitcnt vmcnt(8)
	s_waitcnt lgkmcnt(0)
	s_barrier
	s_waitcnt lgkmcnt(0)
	v_mfma_f32_16x16x32_bf16 v[136:139], v[112:115], v[160:163], v[136:139]
	v_mfma_f32_16x16x32_bf16 v[132:135], v[128:131], v[160:163], v[132:135]
	v_mfma_f32_16x16x32_bf16 v[108:111], v[112:115], v[168:171], v[108:111]
	v_mfma_f32_16x16x32_bf16 v[104:107], v[128:131], v[168:171], v[104:107]
	v_mfma_f32_16x16x32_bf16 v[92:95], v[112:115], v[186:189], v[92:95]
	v_mfma_f32_16x16x32_bf16 v[88:91], v[128:131], v[186:189], v[88:91]
	v_mfma_f32_16x16x32_bf16 v[76:79], v[112:115], v[202:205], v[76:79]
	v_mfma_f32_16x16x32_bf16 v[72:75], v[128:131], v[202:205], v[72:75]
	v_mfma_f32_16x16x32_bf16 v[136:139], v[120:123], v[164:167], v[136:139]
	v_mfma_f32_16x16x32_bf16 v[132:135], v[140:143], v[164:167], v[132:135]
	v_mfma_f32_16x16x32_bf16 v[108:111], v[120:123], v[172:175], v[108:111]
	v_mfma_f32_16x16x32_bf16 v[104:107], v[140:143], v[172:175], v[104:107]
	v_mfma_f32_16x16x32_bf16 v[92:95], v[120:123], v[198:201], v[92:95]
	v_mfma_f32_16x16x32_bf16 v[88:91], v[140:143], v[198:201], v[88:91]
	v_mfma_f32_16x16x32_bf16 v[76:79], v[120:123], v[206:209], v[76:79]
	v_mfma_f32_16x16x32_bf16 v[72:75], v[140:143], v[206:209], v[72:75]
	v_mfma_f32_16x16x32_bf16 v[124:127], v[144:147], v[160:163], v[124:127]
	v_mfma_f32_16x16x32_bf16 v[116:119], v[152:155], v[160:163], v[116:119]
	v_mfma_f32_16x16x32_bf16 v[100:103], v[144:147], v[168:171], v[100:103]
	v_mfma_f32_16x16x32_bf16 v[96:99], v[152:155], v[168:171], v[96:99]
	v_mfma_f32_16x16x32_bf16 v[84:87], v[144:147], v[186:189], v[84:87]
	v_mfma_f32_16x16x32_bf16 v[80:83], v[152:155], v[186:189], v[80:83]
	v_mfma_f32_16x16x32_bf16 v[68:71], v[144:147], v[202:205], v[68:71]
	v_mfma_f32_16x16x32_bf16 v[64:67], v[152:155], v[202:205], v[64:67]
	v_mfma_f32_16x16x32_bf16 v[124:127], v[148:151], v[164:167], v[124:127]
	v_mfma_f32_16x16x32_bf16 v[116:119], v[156:159], v[164:167], v[116:119]
	v_mfma_f32_16x16x32_bf16 v[100:103], v[148:151], v[172:175], v[100:103]
	v_mfma_f32_16x16x32_bf16 v[96:99], v[156:159], v[172:175], v[96:99]
	v_mfma_f32_16x16x32_bf16 v[84:87], v[148:151], v[198:201], v[84:87]
	v_mfma_f32_16x16x32_bf16 v[80:83], v[156:159], v[198:201], v[80:83]
	v_mfma_f32_16x16x32_bf16 v[68:71], v[148:151], v[206:209], v[68:71]
	v_mfma_f32_16x16x32_bf16 v[64:67], v[156:159], v[206:209], v[64:67]
	s_barrier
	s_add_i32 s2, s30, s19
	s_add_i32 m0, s2, 0xffffff80
	ds_read_b128 v[160:163], v231 offset:49152
	ds_read_b128 v[164:167], v231 offset:50176
	ds_read_b128 v[168:171], v231 offset:51200
	ds_read_b128 v[172:175], v231 offset:52224
	ds_read_b128 v[186:189], v231 offset:53248
	ds_read_b128 v[198:201], v231 offset:54272
	ds_read_b128 v[202:205], v231 offset:55296
	ds_read_b128 v[206:209], v231 offset:56320
	global_load_lds_dwordx4 v192, s[6:7] offset:128
	s_add_i32 m0, s2, 0x1f80
	s_add_u32 s2, s6, 0x40080
	global_load_lds_dwordx4 v176, s[6:7] offset:128
	s_addc_u32 s3, s7, 0
	s_add_i32 s6, s31, s19
	s_mov_b32 m0, s6
	s_nop 0
	global_load_lds_dwordx4 v192, s[2:3]
	s_add_i32 m0, s6, 0x2000
	s_nop 0
	global_load_lds_dwordx4 v176, s[2:3]
	s_add_i32 m0, s65, 0xffffff80
	s_nop 0
	global_load_lds_dwordx4 v180, s[84:85] offset:128
	s_add_i32 m0, s80, 0xffffff80
	s_nop 0
	global_load_lds_dwordx4 v178, s[84:85] offset:128
	s_waitcnt vmcnt(8)
	s_waitcnt lgkmcnt(0)
	s_barrier
	s_waitcnt lgkmcnt(0)
	v_mfma_f32_16x16x32_bf16 v[60:63], v[112:115], v[160:163], v[60:63]
	v_mfma_f32_16x16x32_bf16 v[56:59], v[128:131], v[160:163], v[56:59]
	v_mfma_f32_16x16x32_bf16 v[44:47], v[112:115], v[168:171], v[44:47]
	v_mfma_f32_16x16x32_bf16 v[40:43], v[128:131], v[168:171], v[40:43]
	v_mfma_f32_16x16x32_bf16 v[28:31], v[112:115], v[186:189], v[28:31]
	v_mfma_f32_16x16x32_bf16 v[24:27], v[128:131], v[186:189], v[24:27]
	v_mfma_f32_16x16x32_bf16 v[12:15], v[112:115], v[202:205], v[12:15]
	v_mfma_f32_16x16x32_bf16 v[8:11], v[128:131], v[202:205], v[8:11]
	v_mfma_f32_16x16x32_bf16 v[60:63], v[120:123], v[164:167], v[60:63]
	v_mfma_f32_16x16x32_bf16 v[56:59], v[140:143], v[164:167], v[56:59]
	v_mfma_f32_16x16x32_bf16 v[44:47], v[120:123], v[172:175], v[44:47]
	v_mfma_f32_16x16x32_bf16 v[40:43], v[140:143], v[172:175], v[40:43]
	v_mfma_f32_16x16x32_bf16 v[28:31], v[120:123], v[198:201], v[28:31]
	v_mfma_f32_16x16x32_bf16 v[24:27], v[140:143], v[198:201], v[24:27]
	v_mfma_f32_16x16x32_bf16 v[12:15], v[120:123], v[206:209], v[12:15]
	v_mfma_f32_16x16x32_bf16 v[8:11], v[140:143], v[206:209], v[8:11]
	v_mfma_f32_16x16x32_bf16 v[52:55], v[144:147], v[160:163], v[52:55]
	v_mfma_f32_16x16x32_bf16 v[48:51], v[152:155], v[160:163], v[48:51]
	v_mfma_f32_16x16x32_bf16 v[36:39], v[144:147], v[168:171], v[36:39]
	v_mfma_f32_16x16x32_bf16 v[32:35], v[152:155], v[168:171], v[32:35]
	v_mfma_f32_16x16x32_bf16 v[20:23], v[144:147], v[186:189], v[20:23]
	v_mfma_f32_16x16x32_bf16 v[16:19], v[152:155], v[186:189], v[16:19]
	v_mfma_f32_16x16x32_bf16 v[4:7], v[144:147], v[202:205], v[4:7]
	v_mfma_f32_16x16x32_bf16 v[0:3], v[152:155], v[202:205], v[0:3]
	v_mfma_f32_16x16x32_bf16 v[52:55], v[148:151], v[164:167], v[52:55]
	v_mfma_f32_16x16x32_bf16 v[48:51], v[156:159], v[164:167], v[48:51]
	v_mfma_f32_16x16x32_bf16 v[36:39], v[148:151], v[172:175], v[36:39]
	v_mfma_f32_16x16x32_bf16 v[32:35], v[156:159], v[172:175], v[32:35]
	v_mfma_f32_16x16x32_bf16 v[20:23], v[148:151], v[198:201], v[20:23]
	v_mfma_f32_16x16x32_bf16 v[16:19], v[156:159], v[198:201], v[16:19]
	v_mfma_f32_16x16x32_bf16 v[4:7], v[148:151], v[206:209], v[4:7]
	v_mfma_f32_16x16x32_bf16 v[0:3], v[156:159], v[206:209], v[0:3]
	s_barrier
	s_add_i32 s95, s95, 2
	s_add_u32 s93, s93, 0x100
	s_addc_u32 s94, s94, 0
	s_add_u32 s0, s0, 0x100
	s_addc_u32 s1, s1, 0
	s_cmp_gt_u32 s95, 13
	s_cbranch_scc0 .LBB0_634
	s_and_b64 vcc, exec, s[12:13]
	s_cbranch_vccz .LBB0_637
	s_barrier

; #define PG8_STAGE(bufoff, gbase, voff) do { _Pragma("unroll") for (int _i = 0; _i < 2; ++_i) \
;         __builtin_amdgcn_global_load_lds((const unsigned*)((const char*)(gbase) + (voff)[_i]), (PG8_LAS unsigned*)(lds + (bufoff) + ldsw + _i * 8192), 16, 0, 0); } while (0)
; #define PG8_LDA(dst, b, h) do { _Pragma("unroll") for (int m = 0; m < 4; ++m) _Pragma("unroll") for (int k = 0; k < 2; ++k) dst[m][k] = *(const PG8_LAS bf16x8*)(lds + PG8_SA(b, h) + aoff + m * 2048 + k * 1024); } while (0)
; #define PG8_LDB(dst, b, h) do { _Pragma("unroll") for (int n = 0; n < 2; ++n) _Pragma("unroll") for (int k = 0; k < 2; ++k) dst[n][k] = *(const PG8_LAS bf16x8*)(lds + PG8_SB(b, h) + boff + n * 2048 + k * 1024); } while (0)
; #define PG8_SCHED __builtin_amdgcn_sched_barrier(0)
; template <class Epi, class Sched, bool ALIGN_EPI = false, bool SP2 = false>
; __device__ __forceinline__ void gemm_phase(PG8_LAS unsigned char* lds, const Gemm g, const Sched& S, const Epi& E) {
;     ...
;         const bool has_next = S.next(ui + 1, nxt);
;         const char* nA = has_next ? (const char*)g.A + (size_t)nxt.pm * tstepA : cA; const char* nB = has_next ? (const char*)g.Bt + (size_t)nxt.pn * tstepB : cB;
;         for (int t = 0; t < nt; t += 2) {
;             const bool last = (t == nt - 2);
;             const char* a1 = cA + (size_t)(t + 1) * kstep;
;             const char* a2 = last ? nA : cA + (size_t)(t + 2) * kstep; const char* b2 = last ? nB : cB + (size_t)(t + 2) * kstep;
;             const char* a3 = a2 + kstep; const char* b3 = b2 + kstep;
;             if (last && has_next) S.a_ready(nxt);
;             if constexpr (SP2) {
;             PG8_LDB(B0, 0, 0); PG8_LDB(B1, 0, 1); PG8_SCHED; PG8_LDA(At, 0, 0); PG8_STAGE(PG8_SA(1, 1), a1 + hstepA, voffA);
;     ...
; #pragma unroll
;         for (int a = 0; a < 2; ++a)
; #pragma unroll
;             for (int b = 0; b < 2; ++b)
; #pragma unroll
;                 for (int m = 0; m < 4; ++m)
; #pragma unroll
;                     for (int n = 0; n < 2; ++n) acc[a][b][m][n] = (f32x4){0.f, 0.f, 0.f, 0.f};
;         cur = nxt; cA = nA; cB = nB; ++ui;
.LBB0_692:
	s_ashr_i32 s17, s16, 31
	s_lshl_b64 s[2:3], s[16:17], 19
	s_add_u32 s66, s58, s2
	s_addc_u32 s67, s59, s3
	s_and_b64 s[2:3], s[0:1], exec
	s_cselect_b32 s17, s67, s5
	s_cselect_b32 s78, s66, s4
	s_ashr_i32 s15, s14, 31
	s_lshl_b64 s[2:3], s[14:15], 19
	s_add_u32 s82, s38, s2
	s_addc_u32 s83, s41, s3
	s_and_b64 s[2:3], s[0:1], exec
	s_cselect_b32 s15, s83, s85
	s_cselect_b32 s89, s82, s84
	s_add_u32 s90, s84, 0x100
	s_addc_u32 s91, s85, 0
	s_add_u32 s4, s4, 0x40080
	v_mov_b32_e32 v0, 0
	s_addc_u32 s5, s5, 0
	s_mov_b32 s92, -2
	v_mov_b32_e32 v1, v0
	v_mov_b32_e32 v2, v0
	v_mov_b32_e32 v3, v0
	v_mov_b32_e32 v4, v0
	v_mov_b32_e32 v5, v0
	v_mov_b32_e32 v6, v0
	v_mov_b32_e32 v7, v0
	v_mov_b32_e32 v16, v0
	v_mov_b32_e32 v17, v0
	v_mov_b32_e32 v18, v0
	v_mov_b32_e32 v19, v0
	v_mov_b32_e32 v20, v0
	v_mov_b32_e32 v21, v0
	v_mov_b32_e32 v22, v0
	v_mov_b32_e32 v23, v0
	v_mov_b32_e32 v32, v0
	v_mov_b32_e32 v33, v0
	v_mov_b32_e32 v34, v0
	v_mov_b32_e32 v35, v0
	v_mov_b32_e32 v36, v0
	v_mov_b32_e32 v37, v0
	v_mov_b32_e32 v38, v0
	v_mov_b32_e32 v39, v0
	v_mov_b32_e32 v48, v0
	v_mov_b32_e32 v49, v0
	v_mov_b32_e32 v50, v0
	v_mov_b32_e32 v51, v0
	v_mov_b32_e32 v52, v0
	v_mov_b32_e32 v53, v0
	v_mov_b32_e32 v54, v0
	v_mov_b32_e32 v55, v0
	v_mov_b32_e32 v8, v0
	v_mov_b32_e32 v9, v0
	v_mov_b32_e32 v10, v0
	v_mov_b32_e32 v11, v0
	v_mov_b32_e32 v12, v0
	v_mov_b32_e32 v13, v0
	v_mov_b32_e32 v14, v0
	v_mov_b32_e32 v15, v0
	v_mov_b32_e32 v24, v0
	v_mov_b32_e32 v25, v0
	v_mov_b32_e32 v26, v0
	v_mov_b32_e32 v27, v0
	v_mov_b32_e32 v28, v0
	v_mov_b32_e32 v29, v0
	v_mov_b32_e32 v30, v0
	v_mov_b32_e32 v31, v0
	v_mov_b32_e32 v40, v0
	v_mov_b32_e32 v41, v0
	v_mov_b32_e32 v42, v0
	v_mov_b32_e32 v43, v0
	v_mov_b32_e32 v44, v0
	v_mov_b32_e32 v45, v0
	v_mov_b32_e32 v46, v0
	v_mov_b32_e32 v47, v0
	v_mov_b32_e32 v56, v0
	v_mov_b32_e32 v57, v0
	v_mov_b32_e32 v58, v0
	v_mov_b32_e32 v59, v0
	v_mov_b32_e32 v60, v0
	v_mov_b32_e32 v61, v0
	v_mov_b32_e32 v62, v0
	v_mov_b32_e32 v63, v0
	s_waitcnt vmcnt(0)
	v_mov_b32_e32 v64, v0
	v_mov_b32_e32 v65, v0
	v_mov_b32_e32 v66, v0
	v_mov_b32_e32 v67, v0
	v_mov_b32_e32 v68, v0
	v_mov_b32_e32 v69, v0
	v_mov_b32_e32 v70, v0
	v_mov_b32_e32 v71, v0
	v_mov_b32_e32 v80, v0
	v_mov_b32_e32 v81, v0
	v_mov_b32_e32 v82, v0
	v_mov_b32_e32 v83, v0
	v_mov_b32_e32 v84, v0
	v_mov_b32_e32 v85, v0
	v_mov_b32_e32 v86, v0
	v_mov_b32_e32 v87, v0
	v_mov_b32_e32 v96, v0
	v_mov_b32_e32 v97, v0
	v_mov_b32_e32 v98, v0
	v_mov_b32_e32 v99, v0
	v_mov_b32_e32 v100, v0
	v_mov_b32_e32 v101, v0
	v_mov_b32_e32 v102, v0
	v_mov_b32_e32 v103, v0
	v_mov_b32_e32 v112, v0
	v_mov_b32_e32 v113, v0
	v_mov_b32_e32 v114, v0
	v_mov_b32_e32 v115, v0
	v_mov_b32_e32 v116, v0
	v_mov_b32_e32 v117, v0
	v_mov_b32_e32 v118, v0
	v_mov_b32_e32 v119, v0
	v_mov_b32_e32 v72, v0
	v_mov_b32_e32 v73, v0
	v_mov_b32_e32 v74, v0
	v_mov_b32_e32 v75, v0
	v_mov_b32_e32 v76, v0
	v_mov_b32_e32 v77, v0
	v_mov_b32_e32 v78, v0
	v_mov_b32_e32 v79, v0
	v_mov_b32_e32 v88, v0
	v_mov_b32_e32 v89, v0
	v_mov_b32_e32 v90, v0
	v_mov_b32_e32 v91, v0
	v_mov_b32_e32 v92, v0
	v_mov_b32_e32 v93, v0
	v_mov_b32_e32 v94, v0
	v_mov_b32_e32 v95, v0
	v_mov_b32_e32 v104, v0
	v_mov_b32_e32 v105, v0
	v_mov_b32_e32 v106, v0
	v_mov_b32_e32 v107, v0
	v_mov_b32_e32 v108, v0
	v_mov_b32_e32 v109, v0
	v_mov_b32_e32 v110, v0
	v_mov_b32_e32 v111, v0
	v_mov_b32_e32 v120, v0
	v_mov_b32_e32 v121, v0
	v_mov_b32_e32 v122, v0
	v_mov_b32_e32 v123, v0
	v_mov_b32_e32 v124, v0
	v_mov_b32_e32 v125, v0
	v_mov_b32_e32 v126, v0
	v_mov_b32_e32 v127, v0
	v_add_u32_e32 v194, 0x10000, v182
	v_add_u32_e32 v195, 0x14000, v182
	v_add_u32_e32 v196, 0x18000, v182
	v_add_u32_e32 v197, 0x1c000, v182
.LBB0_693:
	s_add_u32 s2, s4, 0xfffc0080
	s_addc_u32 s3, s5, -1
	s_add_i32 s30, 0, 0x10000
	s_cmp_eq_u32 s92, 12
	s_cselect_b32 s87, s17, s3
	s_cselect_b32 s86, s78, s2
	s_cselect_b32 s85, s15, s91
	s_cselect_b32 s84, s89, s90
	s_add_i32 s31, 0, 0x14000
	ds_read_b128 v[128:131], v194
	ds_read_b128 v[132:135], v194 offset:1024
	ds_read_b128 v[136:139], v194 offset:2048
	ds_read_b128 v[140:143], v194 offset:3072
	ds_read_b128 v[144:147], v195
	ds_read_b128 v[148:151], v195 offset:1024
	ds_read_b128 v[152:155], v195 offset:2048
	ds_read_b128 v[166:169], v195 offset:3072
	s_add_i32 m0, s20, 0xc000
	ds_read_b128 v[170:173], v183
	ds_read_b128 v[174:177], v183 offset:1024
	ds_read_b128 v[178:181], v183 offset:2048
	ds_read_b128 v[184:187], v183 offset:3072
	ds_read_b128 v[188:191], v183 offset:4096
	ds_read_b128 v[198:201], v183 offset:5120
	ds_read_b128 v[202:205], v183 offset:6144
	ds_read_b128 v[206:209], v183 offset:7168
	global_load_lds_dwordx4 v164, s[4:5]
	s_add_i32 m0, s20, 0xe000
	s_nop 0
	global_load_lds_dwordx4 v162, s[4:5]
	s_waitcnt vmcnt(8)
	s_waitcnt lgkmcnt(0)
	s_barrier
; #define PG8_STAGE(bufoff, gbase, voff) do { _Pragma("unroll") for (int _i = 0; _i < 2; ++_i) \
;         __builtin_amdgcn_global_load_lds((const unsigned*)((const char*)(gbase) + (voff)[_i]), (PG8_LAS unsigned*)(lds + (bufoff) + ldsw + _i * 8192), 16, 0, 0); } while (0)
; #define PG8_LDA(dst, b, h) do { _Pragma("unroll") for (int m = 0; m < 4; ++m) _Pragma("unroll") for (int k = 0; k < 2; ++k) dst[m][k] = *(const PG8_LAS bf16x8*)(lds + PG8_SA(b, h) + aoff + m * 2048 + k * 1024); } while (0)
; #define PG8_LDB(dst, b, h) do { _Pragma("unroll") for (int n = 0; n < 2; ++n) _Pragma("unroll") for (int k = 0; k < 2; ++k) dst[n][k] = *(const PG8_LAS bf16x8*)(lds + PG8_SB(b, h) + boff + n * 2048 + k * 1024); } while (0)
; #define PG8_MMA(ai, bj, At, Bt) do { __builtin_amdgcn_s_setprio(1); _Pragma("unroll") for (int m = 0; m < 4; ++m) _Pragma("unroll") for (int n = 0; n < 2; ++n) _Pragma("unroll") for (int k = 0; k < 2; ++k) \
;         acc[ai][bj][m][n] = __builtin_amdgcn_mfma_f32_16x16x32_bf16(Bt[n][k], At[m][k], acc[ai][bj][m][n], 0, 0, 0); __builtin_amdgcn_s_setprio(0); } while (0)
; #define PG8_WAIT_V(n) asm volatile("s_waitcnt vmcnt(" #n ")" ::: "memory")
; #define PG8_WAIT_L(n) asm volatile("s_waitcnt lgkmcnt(" #n ")" ::: "memory")
; #define PG8_BAR __builtin_amdgcn_s_barrier()
; #define PG8_SCHED __builtin_amdgcn_sched_barrier(0)
; template <class Epi, class Sched, bool ALIGN_EPI = false, bool SP2 = false>
; __device__ __forceinline__ void gemm_phase(PG8_LAS unsigned char* lds, const Gemm g, const Sched& S, const Epi& E) {
;     ...
;             PG8_LDB(B0, 0, 0); PG8_LDB(B1, 0, 1); PG8_SCHED; PG8_LDA(At, 0, 0); PG8_STAGE(PG8_SA(1, 1), a1 + hstepA, voffA);
;             PG8_WAIT_V(8); PG8_WAIT_L(0); PG8_BAR; PG8_MMA(0, 0, At, B0); PG8_MMA(0, 1, At, B1); PG8_BAR; PG8_SCHED;
;             PG8_LDA(At, 0, 1); PG8_STAGE(PG8_SB(0, 0), b2, voffB); PG8_STAGE(PG8_SB(0, 1), b2 + hstepB, voffB); PG8_STAGE(PG8_SA(0, 0), a2, voffA);
;             PG8_WAIT_V(8); PG8_WAIT_L(0); PG8_BAR; PG8_MMA(1, 0, At, B0); PG8_MMA(1, 1, At, B1); PG8_BAR; PG8_SCHED;
	s_waitcnt lgkmcnt(0)
	v_mfma_f32_16x16x32_bf16 v[124:127], v[128:131], v[170:173], v[124:127]
	v_mfma_f32_16x16x32_bf16 v[120:123], v[136:139], v[170:173], v[120:123]
	v_mfma_f32_16x16x32_bf16 v[108:111], v[128:131], v[178:181], v[108:111]
	v_mfma_f32_16x16x32_bf16 v[104:107], v[136:139], v[178:181], v[104:107]
	v_mfma_f32_16x16x32_bf16 v[92:95], v[128:131], v[188:191], v[92:95]
	v_mfma_f32_16x16x32_bf16 v[88:91], v[136:139], v[188:191], v[88:91]
	v_mfma_f32_16x16x32_bf16 v[76:79], v[128:131], v[202:205], v[76:79]
	v_mfma_f32_16x16x32_bf16 v[72:75], v[136:139], v[202:205], v[72:75]
	v_mfma_f32_16x16x32_bf16 v[124:127], v[132:135], v[174:177], v[124:127]
	v_mfma_f32_16x16x32_bf16 v[120:123], v[140:143], v[174:177], v[120:123]
	v_mfma_f32_16x16x32_bf16 v[108:111], v[132:135], v[184:187], v[108:111]
	v_mfma_f32_16x16x32_bf16 v[104:107], v[140:143], v[184:187], v[104:107]
	v_mfma_f32_16x16x32_bf16 v[92:95], v[132:135], v[198:201], v[92:95]
	v_mfma_f32_16x16x32_bf16 v[88:91], v[140:143], v[198:201], v[88:91]
	v_mfma_f32_16x16x32_bf16 v[76:79], v[132:135], v[206:209], v[76:79]
	v_mfma_f32_16x16x32_bf16 v[72:75], v[140:143], v[206:209], v[72:75]
	v_mfma_f32_16x16x32_bf16 v[116:119], v[144:147], v[170:173], v[116:119]
	v_mfma_f32_16x16x32_bf16 v[112:115], v[152:155], v[170:173], v[112:115]
	v_mfma_f32_16x16x32_bf16 v[100:103], v[144:147], v[178:181], v[100:103]
	v_mfma_f32_16x16x32_bf16 v[96:99], v[152:155], v[178:181], v[96:99]
	v_mfma_f32_16x16x32_bf16 v[84:87], v[144:147], v[188:191], v[84:87]
	v_mfma_f32_16x16x32_bf16 v[80:83], v[152:155], v[188:191], v[80:83]
	v_mfma_f32_16x16x32_bf16 v[68:71], v[144:147], v[202:205], v[68:71]
	v_mfma_f32_16x16x32_bf16 v[64:67], v[152:155], v[202:205], v[64:67]
	v_mfma_f32_16x16x32_bf16 v[116:119], v[148:151], v[174:177], v[116:119]
	v_mfma_f32_16x16x32_bf16 v[112:115], v[166:169], v[174:177], v[112:115]
	v_mfma_f32_16x16x32_bf16 v[100:103], v[148:151], v[184:187], v[100:103]
	v_mfma_f32_16x16x32_bf16 v[96:99], v[166:169], v[184:187], v[96:99]
	v_mfma_f32_16x16x32_bf16 v[84:87], v[148:151], v[198:201], v[84:87]
	v_mfma_f32_16x16x32_bf16 v[80:83], v[166:169], v[198:201], v[80:83]
	v_mfma_f32_16x16x32_bf16 v[68:71], v[148:151], v[206:209], v[68:71]
	v_mfma_f32_16x16x32_bf16 v[64:67], v[166:169], v[206:209], v[64:67]
	s_barrier
	s_add_i32 s2, s30, s19
	s_mov_b32 m0, s2
	ds_read_b128 v[170:173], v183 offset:16384
	ds_read_b128 v[174:177], v183 offset:17408
	ds_read_b128 v[178:181], v183 offset:18432
	ds_read_b128 v[184:187], v183 offset:19456
	ds_read_b128 v[188:191], v183 offset:20480
	ds_read_b128 v[198:201], v183 offset:21504
	ds_read_b128 v[202:205], v183 offset:22528
	ds_read_b128 v[206:209], v183 offset:23552
	global_load_lds_dwordx4 v192, s[84:85]
	s_add_i32 m0, s2, 0x2000
	s_add_u32 s2, s84, 0x40000
	s_addc_u32 s3, s85, 0
	s_add_i32 s30, s31, s19
	global_load_lds_dwordx4 v156, s[84:85]
	s_mov_b32 m0, s30
	s_nop 0
	global_load_lds_dwordx4 v192, s[2:3]
	s_add_i32 m0, s30, 0x2000
	s_nop 0
	global_load_lds_dwordx4 v156, s[2:3]
	s_mov_b32 m0, s20
	s_nop 0
	global_load_lds_dwordx4 v160, s[86:87]
	s_mov_b32 m0, s21
	s_nop 0
	global_load_lds_dwordx4 v158, s[86:87]
	s_waitcnt vmcnt(8)
	s_waitcnt lgkmcnt(0)
	s_barrier
	s_waitcnt lgkmcnt(0)
	v_mfma_f32_16x16x32_bf16 v[60:63], v[128:131], v[170:173], v[60:63]
	v_mfma_f32_16x16x32_bf16 v[56:59], v[136:139], v[170:173], v[56:59]
	v_mfma_f32_16x16x32_bf16 v[44:47], v[128:131], v[178:181], v[44:47]
	v_mfma_f32_16x16x32_bf16 v[40:43], v[136:139], v[178:181], v[40:43]
	v_mfma_f32_16x16x32_bf16 v[28:31], v[128:131], v[188:191], v[28:31]
	v_mfma_f32_16x16x32_bf16 v[24:27], v[136:139], v[188:191], v[24:27]
	v_mfma_f32_16x16x32_bf16 v[12:15], v[128:131], v[202:205], v[12:15]
	v_mfma_f32_16x16x32_bf16 v[8:11], v[136:139], v[202:205], v[8:11]
	v_mfma_f32_16x16x32_bf16 v[60:63], v[132:135], v[174:177], v[60:63]
	v_mfma_f32_16x16x32_bf16 v[56:59], v[140:143], v[174:177], v[56:59]
	v_mfma_f32_16x16x32_bf16 v[44:47], v[132:135], v[184:187], v[44:47]
	v_mfma_f32_16x16x32_bf16 v[40:43], v[140:143], v[184:187], v[40:43]
	v_mfma_f32_16x16x32_bf16 v[28:31], v[132:135], v[198:201], v[28:31]
	v_mfma_f32_16x16x32_bf16 v[24:27], v[140:143], v[198:201], v[24:27]
	v_mfma_f32_16x16x32_bf16 v[12:15], v[132:135], v[206:209], v[12:15]
	v_mfma_f32_16x16x32_bf16 v[8:11], v[140:143], v[206:209], v[8:11]
	v_mfma_f32_16x16x32_bf16 v[52:55], v[144:147], v[170:173], v[52:55]
	v_mfma_f32_16x16x32_bf16 v[48:51], v[152:155], v[170:173], v[48:51]
	v_mfma_f32_16x16x32_bf16 v[36:39], v[144:147], v[178:181], v[36:39]
	v_mfma_f32_16x16x32_bf16 v[32:35], v[152:155], v[178:181], v[32:35]
	v_mfma_f32_16x16x32_bf16 v[20:23], v[144:147], v[188:191], v[20:23]
	v_mfma_f32_16x16x32_bf16 v[16:19], v[152:155], v[188:191], v[16:19]
	v_mfma_f32_16x16x32_bf16 v[4:7], v[144:147], v[202:205], v[4:7]
	v_mfma_f32_16x16x32_bf16 v[0:3], v[152:155], v[202:205], v[0:3]
	v_mfma_f32_16x16x32_bf16 v[52:55], v[148:151], v[174:177], v[52:55]
	v_mfma_f32_16x16x32_bf16 v[48:51], v[166:169], v[174:177], v[48:51]
	v_mfma_f32_16x16x32_bf16 v[36:39], v[148:151], v[184:187], v[36:39]
	v_mfma_f32_16x16x32_bf16 v[32:35], v[166:169], v[184:187], v[32:35]
	v_mfma_f32_16x16x32_bf16 v[20:23], v[148:151], v[198:201], v[20:23]
	v_mfma_f32_16x16x32_bf16 v[16:19], v[166:169], v[198:201], v[16:19]
	v_mfma_f32_16x16x32_bf16 v[4:7], v[148:151], v[206:209], v[4:7]
	v_mfma_f32_16x16x32_bf16 v[0:3], v[166:169], v[206:209], v[0:3]
	s_barrier
; #define PG8_STAGE(bufoff, gbase, voff) do { _Pragma("unroll") for (int _i = 0; _i < 2; ++_i) \
;         __builtin_amdgcn_global_load_lds((const unsigned*)((const char*)(gbase) + (voff)[_i]), (PG8_LAS unsigned*)(lds + (bufoff) + ldsw + _i * 8192), 16, 0, 0); } while (0)
; #define PG8_LDA(dst, b, h) do { _Pragma("unroll") for (int m = 0; m < 4; ++m) _Pragma("unroll") for (int k = 0; k < 2; ++k) dst[m][k] = *(const PG8_LAS bf16x8*)(lds + PG8_SA(b, h) + aoff + m * 2048 + k * 1024); } while (0)
; #define PG8_LDB(dst, b, h) do { _Pragma("unroll") for (int n = 0; n < 2; ++n) _Pragma("unroll") for (int k = 0; k < 2; ++k) dst[n][k] = *(const PG8_LAS bf16x8*)(lds + PG8_SB(b, h) + boff + n * 2048 + k * 1024); } while (0)
; #define PG8_MMA(ai, bj, At, Bt) do { __builtin_amdgcn_s_setprio(1); _Pragma("unroll") for (int m = 0; m < 4; ++m) _Pragma("unroll") for (int n = 0; n < 2; ++n) _Pragma("unroll") for (int k = 0; k < 2; ++k) \
;         acc[ai][bj][m][n] = __builtin_amdgcn_mfma_f32_16x16x32_bf16(Bt[n][k], At[m][k], acc[ai][bj][m][n], 0, 0, 0); __builtin_amdgcn_s_setprio(0); } while (0)
; #define PG8_WAIT_V(n) asm volatile("s_waitcnt vmcnt(" #n ")" ::: "memory")
; #define PG8_WAIT_L(n) asm volatile("s_waitcnt lgkmcnt(" #n ")" ::: "memory")
; #define PG8_BAR __builtin_amdgcn_s_barrier()
; #define PG8_SCHED __builtin_amdgcn_sched_barrier(0)
; template <class Epi, class Sched, bool ALIGN_EPI = false, bool SP2 = false>
; __device__ __forceinline__ void gemm_phase(PG8_LAS unsigned char* lds, const Gemm g, const Sched& S, const Epi& E) {
;     ...
;             PG8_LDB(B0, 1, 0); PG8_LDB(B1, 1, 1); PG8_SCHED; PG8_LDA(At, 1, 0); PG8_STAGE(PG8_SA(0, 1), a2 + hstepA, voffA);
;             PG8_WAIT_V(8); PG8_WAIT_L(0); PG8_BAR; PG8_MMA(0, 0, At, B0); PG8_MMA(0, 1, At, B1); PG8_BAR; PG8_SCHED;
;             PG8_LDA(At, 1, 1); PG8_STAGE(PG8_SB(1, 0), b3, voffB); PG8_STAGE(PG8_SB(1, 1), b3 + hstepB, voffB); PG8_STAGE(PG8_SA(1, 0), a3, voffA);
;             PG8_WAIT_V(8); PG8_WAIT_L(0); PG8_BAR; PG8_MMA(1, 0, At, B0); PG8_MMA(1, 1, At, B1); PG8_BAR; PG8_SCHED;
	s_add_i32 s30, 0, 0x18000
	s_add_i32 s31, 0, 0x1c000
	ds_read_b128 v[128:131], v196
	ds_read_b128 v[132:135], v196 offset:1024
	ds_read_b128 v[136:139], v196 offset:2048
	ds_read_b128 v[140:143], v196 offset:3072
	ds_read_b128 v[144:147], v197
	ds_read_b128 v[148:151], v197 offset:1024
	ds_read_b128 v[152:155], v197 offset:2048
	ds_read_b128 v[166:169], v197 offset:3072
	s_add_u32 s2, s86, 0x40000
	s_addc_u32 s3, s87, 0
	s_mov_b32 m0, s34
	ds_read_b128 v[170:173], v183 offset:32768
	ds_read_b128 v[174:177], v183 offset:33792
	ds_read_b128 v[178:181], v183 offset:34816
	ds_read_b128 v[184:187], v183 offset:35840
	ds_read_b128 v[188:191], v183 offset:36864
	ds_read_b128 v[198:201], v183 offset:37888
	ds_read_b128 v[202:205], v183 offset:38912
	ds_read_b128 v[206:209], v183 offset:39936
	global_load_lds_dwordx4 v160, s[2:3]
	s_mov_b32 m0, s45
	s_nop 0
	global_load_lds_dwordx4 v158, s[2:3]
	s_waitcnt vmcnt(8)
	s_waitcnt lgkmcnt(0)
	s_barrier
	s_waitcnt lgkmcnt(0)
	v_mfma_f32_16x16x32_bf16 v[124:127], v[128:131], v[170:173], v[124:127]
	v_mfma_f32_16x16x32_bf16 v[120:123], v[136:139], v[170:173], v[120:123]
	v_mfma_f32_16x16x32_bf16 v[108:111], v[128:131], v[178:181], v[108:111]
	v_mfma_f32_16x16x32_bf16 v[104:107], v[136:139], v[178:181], v[104:107]
	v_mfma_f32_16x16x32_bf16 v[92:95], v[128:131], v[188:191], v[92:95]
	v_mfma_f32_16x16x32_bf16 v[88:91], v[136:139], v[188:191], v[88:91]
	v_mfma_f32_16x16x32_bf16 v[76:79], v[128:131], v[202:205], v[76:79]
	v_mfma_f32_16x16x32_bf16 v[72:75], v[136:139], v[202:205], v[72:75]
	v_mfma_f32_16x16x32_bf16 v[124:127], v[132:135], v[174:177], v[124:127]
	v_mfma_f32_16x16x32_bf16 v[120:123], v[140:143], v[174:177], v[120:123]
	v_mfma_f32_16x16x32_bf16 v[108:111], v[132:135], v[184:187], v[108:111]
	v_mfma_f32_16x16x32_bf16 v[104:107], v[140:143], v[184:187], v[104:107]
	v_mfma_f32_16x16x32_bf16 v[92:95], v[132:135], v[198:201], v[92:95]
	v_mfma_f32_16x16x32_bf16 v[88:91], v[140:143], v[198:201], v[88:91]
	v_mfma_f32_16x16x32_bf16 v[76:79], v[132:135], v[206:209], v[76:79]
	v_mfma_f32_16x16x32_bf16 v[72:75], v[140:143], v[206:209], v[72:75]
	v_mfma_f32_16x16x32_bf16 v[116:119], v[144:147], v[170:173], v[116:119]
	v_mfma_f32_16x16x32_bf16 v[112:115], v[152:155], v[170:173], v[112:115]
	v_mfma_f32_16x16x32_bf16 v[100:103], v[144:147], v[178:181], v[100:103]
	v_mfma_f32_16x16x32_bf16 v[96:99], v[152:155], v[178:181], v[96:99]
	v_mfma_f32_16x16x32_bf16 v[84:87], v[144:147], v[188:191], v[84:87]
	v_mfma_f32_16x16x32_bf16 v[80:83], v[152:155], v[188:191], v[80:83]
	v_mfma_f32_16x16x32_bf16 v[68:71], v[144:147], v[202:205], v[68:71]
	v_mfma_f32_16x16x32_bf16 v[64:67], v[152:155], v[202:205], v[64:67]
	v_mfma_f32_16x16x32_bf16 v[116:119], v[148:151], v[174:177], v[116:119]
	v_mfma_f32_16x16x32_bf16 v[112:115], v[166:169], v[174:177], v[112:115]
	v_mfma_f32_16x16x32_bf16 v[100:103], v[148:151], v[184:187], v[100:103]
	v_mfma_f32_16x16x32_bf16 v[96:99], v[166:169], v[184:187], v[96:99]
	v_mfma_f32_16x16x32_bf16 v[84:87], v[148:151], v[198:201], v[84:87]
	v_mfma_f32_16x16x32_bf16 v[80:83], v[166:169], v[198:201], v[80:83]
	v_mfma_f32_16x16x32_bf16 v[68:71], v[148:151], v[206:209], v[68:71]
	v_mfma_f32_16x16x32_bf16 v[64:67], v[166:169], v[206:209], v[64:67]
	s_barrier
	s_add_i32 s2, s30, s19
	s_add_i32 m0, s2, 0xffffff80
	ds_read_b128 v[170:173], v183 offset:49152
	ds_read_b128 v[174:177], v183 offset:50176
	ds_read_b128 v[178:181], v183 offset:51200
	ds_read_b128 v[184:187], v183 offset:52224
	ds_read_b128 v[188:191], v183 offset:53248
	ds_read_b128 v[198:201], v183 offset:54272
	ds_read_b128 v[202:205], v183 offset:55296
	ds_read_b128 v[206:209], v183 offset:56320
	global_load_lds_dwordx4 v192, s[84:85] offset:128
	s_add_i32 m0, s2, 0x1f80
	s_add_u32 s2, s84, 0x40080
	s_addc_u32 s3, s85, 0
	s_add_i32 s30, s31, s19
	global_load_lds_dwordx4 v156, s[84:85] offset:128
	s_mov_b32 m0, s30
	s_nop 0
	global_load_lds_dwordx4 v192, s[2:3]
	s_add_i32 m0, s30, 0x2000
	s_nop 0
	global_load_lds_dwordx4 v156, s[2:3]
	s_add_i32 m0, s63, 0xffffff80
	s_nop 0
	global_load_lds_dwordx4 v160, s[86:87] offset:128
	s_add_i32 m0, s64, 0xffffff80
	s_nop 0
	global_load_lds_dwordx4 v158, s[86:87] offset:128
	s_waitcnt vmcnt(8)
	s_waitcnt lgkmcnt(0)
	s_barrier
	s_waitcnt lgkmcnt(0)
	v_mfma_f32_16x16x32_bf16 v[60:63], v[128:131], v[170:173], v[60:63]
	v_mfma_f32_16x16x32_bf16 v[56:59], v[136:139], v[170:173], v[56:59]
	v_mfma_f32_16x16x32_bf16 v[44:47], v[128:131], v[178:181], v[44:47]
	v_mfma_f32_16x16x32_bf16 v[40:43], v[136:139], v[178:181], v[40:43]
	v_mfma_f32_16x16x32_bf16 v[28:31], v[128:131], v[188:191], v[28:31]
	v_mfma_f32_16x16x32_bf16 v[24:27], v[136:139], v[188:191], v[24:27]
	v_mfma_f32_16x16x32_bf16 v[12:15], v[128:131], v[202:205], v[12:15]
	v_mfma_f32_16x16x32_bf16 v[8:11], v[136:139], v[202:205], v[8:11]
	v_mfma_f32_16x16x32_bf16 v[60:63], v[132:135], v[174:177], v[60:63]
	v_mfma_f32_16x16x32_bf16 v[56:59], v[140:143], v[174:177], v[56:59]
	v_mfma_f32_16x16x32_bf16 v[44:47], v[132:135], v[184:187], v[44:47]
	v_mfma_f32_16x16x32_bf16 v[40:43], v[140:143], v[184:187], v[40:43]
	v_mfma_f32_16x16x32_bf16 v[28:31], v[132:135], v[198:201], v[28:31]
	v_mfma_f32_16x16x32_bf16 v[24:27], v[140:143], v[198:201], v[24:27]
	v_mfma_f32_16x16x32_bf16 v[12:15], v[132:135], v[206:209], v[12:15]
	v_mfma_f32_16x16x32_bf16 v[8:11], v[140:143], v[206:209], v[8:11]
	v_mfma_f32_16x16x32_bf16 v[52:55], v[144:147], v[170:173], v[52:55]
	v_mfma_f32_16x16x32_bf16 v[48:51], v[152:155], v[170:173], v[48:51]
	v_mfma_f32_16x16x32_bf16 v[36:39], v[144:147], v[178:181], v[36:39]
	v_mfma_f32_16x16x32_bf16 v[32:35], v[152:155], v[178:181], v[32:35]
	v_mfma_f32_16x16x32_bf16 v[20:23], v[144:147], v[188:191], v[20:23]
	v_mfma_f32_16x16x32_bf16 v[16:19], v[152:155], v[188:191], v[16:19]
	v_mfma_f32_16x16x32_bf16 v[4:7], v[144:147], v[202:205], v[4:7]
	v_mfma_f32_16x16x32_bf16 v[0:3], v[152:155], v[202:205], v[0:3]
	v_mfma_f32_16x16x32_bf16 v[52:55], v[148:151], v[174:177], v[52:55]
	v_mfma_f32_16x16x32_bf16 v[48:51], v[166:169], v[174:177], v[48:51]
	v_mfma_f32_16x16x32_bf16 v[36:39], v[148:151], v[184:187], v[36:39]
	v_mfma_f32_16x16x32_bf16 v[32:35], v[166:169], v[184:187], v[32:35]
	v_mfma_f32_16x16x32_bf16 v[20:23], v[148:151], v[198:201], v[20:23]
	v_mfma_f32_16x16x32_bf16 v[16:19], v[166:169], v[198:201], v[16:19]
	v_mfma_f32_16x16x32_bf16 v[4:7], v[148:151], v[206:209], v[4:7]
	v_mfma_f32_16x16x32_bf16 v[0:3], v[166:169], v[206:209], v[0:3]
	s_barrier
	s_add_i32 s92, s92, 2
	s_add_u32 s90, s90, 0x100
	s_addc_u32 s91, s91, 0
	s_add_u32 s4, s4, 0x100
	s_addc_u32 s5, s5, 0
	s_cmp_gt_u32 s92, 13
	s_cbranch_scc0 .LBB0_693
	s_and_b64 vcc, exec, s[12:13]
	s_cbranch_vccz .LBB0_696
	s_barrier

; #define PG8_STAGE(bufoff, gbase, voff) do { _Pragma("unroll") for (int _i = 0; _i < 2; ++_i) \
;         __builtin_amdgcn_global_load_lds((const unsigned*)((const char*)(gbase) + (voff)[_i]), (PG8_LAS unsigned*)(lds + (bufoff) + ldsw + _i * 8192), 16, 0, 0); } while (0)
; #define PG8_LDA(dst, b, h) do { _Pragma("unroll") for (int m = 0; m < 4; ++m) _Pragma("unroll") for (int k = 0; k < 2; ++k) dst[m][k] = *(const PG8_LAS bf16x8*)(lds + PG8_SA(b, h) + aoff + m * 2048 + k * 1024); } while (0)
; #define PG8_LDB(dst, b, h) do { _Pragma("unroll") for (int n = 0; n < 2; ++n) _Pragma("unroll") for (int k = 0; k < 2; ++k) dst[n][k] = *(const PG8_LAS bf16x8*)(lds + PG8_SB(b, h) + boff + n * 2048 + k * 1024); } while (0)
; #define PG8_SCHED __builtin_amdgcn_sched_barrier(0)
; template <class Epi, class Sched, bool ALIGN_EPI = false, bool SP2 = false>
; __device__ __forceinline__ void gemm_phase(PG8_LAS unsigned char* lds, const Gemm g, const Sched& S, const Epi& E) {
;     ...
;             const char* a1 = cA + (size_t)(t + 1) * kstep;
;             const char* a2 = last ? nA : cA + (size_t)(t + 2) * kstep; const char* b2 = last ? nB : cB + (size_t)(t + 2) * kstep;
;             const char* a3 = a2 + kstep; const char* b3 = b2 + kstep;
;             if (last && has_next) S.a_ready(nxt);
;             if constexpr (SP2) {
;             PG8_LDB(B0, 0, 0); PG8_LDB(B1, 0, 1); PG8_SCHED; PG8_LDA(At, 0, 0); PG8_STAGE(PG8_SA(1, 1), a1 + hstepA, voffA);
;     ...
; #pragma unroll
;         for (int a = 0; a < 2; ++a)
; #pragma unroll
;             for (int b = 0; b < 2; ++b)
; #pragma unroll
;                 for (int m = 0; m < 4; ++m)
; #pragma unroll
;                     for (int n = 0; n < 2; ++n) acc[a][b][m][n] = (f32x4){0.f, 0.f, 0.f, 0.f};
;         cur = nxt; cA = nA; cB = nB; ++ui;
.LBB0_723:
	s_add_u32 vcc_lo, s82, 0x100
	s_addc_u32 vcc_hi, s83, 0
	s_add_u32 s82, s84, 0x80
	v_mov_b32_e32 v0, 0
	s_addc_u32 s83, s85, 0
	s_mov_b32 s84, 0
	v_mov_b32_e32 v1, v0
	v_mov_b32_e32 v2, v0
	v_mov_b32_e32 v3, v0
	v_mov_b32_e32 v4, v0
	v_mov_b32_e32 v5, v0
	v_mov_b32_e32 v6, v0
	v_mov_b32_e32 v7, v0
	v_mov_b32_e32 v16, v0
	v_mov_b32_e32 v17, v0
	v_mov_b32_e32 v18, v0
	v_mov_b32_e32 v19, v0
	v_mov_b32_e32 v20, v0
	v_mov_b32_e32 v21, v0
	v_mov_b32_e32 v22, v0
	v_mov_b32_e32 v23, v0
	v_mov_b32_e32 v32, v0
	v_mov_b32_e32 v33, v0
	v_mov_b32_e32 v34, v0
	v_mov_b32_e32 v35, v0
	v_mov_b32_e32 v36, v0
	v_mov_b32_e32 v37, v0
	v_mov_b32_e32 v38, v0
	v_mov_b32_e32 v39, v0
	v_mov_b32_e32 v48, v0
	v_mov_b32_e32 v49, v0
	v_mov_b32_e32 v50, v0
	v_mov_b32_e32 v51, v0
	v_mov_b32_e32 v52, v0
	v_mov_b32_e32 v53, v0
	v_mov_b32_e32 v54, v0
	v_mov_b32_e32 v55, v0
	v_mov_b32_e32 v8, v0
	v_mov_b32_e32 v9, v0
	v_mov_b32_e32 v10, v0
	v_mov_b32_e32 v11, v0
	v_mov_b32_e32 v12, v0
	v_mov_b32_e32 v13, v0
	v_mov_b32_e32 v14, v0
	v_mov_b32_e32 v15, v0
	v_mov_b32_e32 v24, v0
	v_mov_b32_e32 v25, v0
	v_mov_b32_e32 v26, v0
	v_mov_b32_e32 v27, v0
	v_mov_b32_e32 v28, v0
	v_mov_b32_e32 v29, v0
	v_mov_b32_e32 v30, v0
	v_mov_b32_e32 v31, v0
	v_mov_b32_e32 v40, v0
	v_mov_b32_e32 v41, v0
	v_mov_b32_e32 v42, v0
	v_mov_b32_e32 v43, v0
	v_mov_b32_e32 v44, v0
	v_mov_b32_e32 v45, v0
	v_mov_b32_e32 v46, v0
	v_mov_b32_e32 v47, v0
	v_mov_b32_e32 v56, v0
	v_mov_b32_e32 v57, v0
	v_mov_b32_e32 v58, v0
	v_mov_b32_e32 v59, v0
	v_mov_b32_e32 v60, v0
	v_mov_b32_e32 v61, v0
	v_mov_b32_e32 v62, v0
	v_mov_b32_e32 v63, v0
	s_waitcnt vmcnt(0)
	v_mov_b32_e32 v64, v0
	v_mov_b32_e32 v65, v0
	v_mov_b32_e32 v66, v0
	v_mov_b32_e32 v67, v0
	v_mov_b32_e32 v68, v0
	v_mov_b32_e32 v69, v0
	v_mov_b32_e32 v70, v0
	v_mov_b32_e32 v71, v0
	v_mov_b32_e32 v80, v0
	v_mov_b32_e32 v81, v0
	v_mov_b32_e32 v82, v0
	v_mov_b32_e32 v83, v0
	v_mov_b32_e32 v84, v0
	v_mov_b32_e32 v85, v0
	v_mov_b32_e32 v86, v0
	v_mov_b32_e32 v87, v0
	v_mov_b32_e32 v96, v0
	v_mov_b32_e32 v97, v0
	v_mov_b32_e32 v98, v0
	v_mov_b32_e32 v99, v0
	v_mov_b32_e32 v100, v0
	v_mov_b32_e32 v101, v0
	v_mov_b32_e32 v102, v0
	v_mov_b32_e32 v103, v0
	v_mov_b32_e32 v116, v0
	v_mov_b32_e32 v117, v0
	v_mov_b32_e32 v118, v0
	v_mov_b32_e32 v119, v0
	v_mov_b32_e32 v120, v0
	v_mov_b32_e32 v121, v0
	v_mov_b32_e32 v122, v0
	v_mov_b32_e32 v123, v0
	v_mov_b32_e32 v72, v0
	v_mov_b32_e32 v73, v0
	v_mov_b32_e32 v74, v0
	v_mov_b32_e32 v75, v0
	v_mov_b32_e32 v76, v0
	v_mov_b32_e32 v77, v0
	v_mov_b32_e32 v78, v0
	v_mov_b32_e32 v79, v0
	v_mov_b32_e32 v88, v0
	v_mov_b32_e32 v89, v0
	v_mov_b32_e32 v90, v0
	v_mov_b32_e32 v91, v0
	v_mov_b32_e32 v92, v0
	v_mov_b32_e32 v93, v0
	v_mov_b32_e32 v94, v0
	v_mov_b32_e32 v95, v0
	v_mov_b32_e32 v104, v0
	v_mov_b32_e32 v105, v0
	v_mov_b32_e32 v106, v0
	v_mov_b32_e32 v107, v0
	v_mov_b32_e32 v108, v0
	v_mov_b32_e32 v109, v0
	v_mov_b32_e32 v110, v0
	v_mov_b32_e32 v111, v0
	v_mov_b32_e32 v132, v0
	v_mov_b32_e32 v133, v0
	v_mov_b32_e32 v134, v0
	v_mov_b32_e32 v135, v0
	v_mov_b32_e32 v140, v0
	v_mov_b32_e32 v141, v0
	v_mov_b32_e32 v142, v0
	v_mov_b32_e32 v143, v0
	v_add_u32_e32 v194, 0x10000, v247
	v_add_u32_e32 v195, 0x14000, v247
	v_add_u32_e32 v196, 0x18000, v247
	v_add_u32_e32 v197, 0x1c000, v247
.LBB0_724:
	s_add_i32 s2, s84, 2
	s_add_u32 s3, s82, 0x80
	s_addc_u32 s30, s83, 0
	s_add_i32 s77, 0, 0x10000
	s_cmp_eq_u32 s93, s84
	s_cselect_b32 s85, s5, s30
	s_cselect_b32 s84, s4, s3
	s_cselect_b32 s31, s67, vcc_hi
	s_cselect_b32 s30, s66, vcc_lo
	s_add_i32 s3, 0, 0x14000
	ds_read_b128 v[112:115], v194
	ds_read_b128 v[124:127], v194 offset:1024
	ds_read_b128 v[128:131], v194 offset:2048
	ds_read_b128 v[136:139], v194 offset:3072
	ds_read_b128 v[144:147], v195
	ds_read_b128 v[148:151], v195 offset:1024
	ds_read_b128 v[152:155], v195 offset:2048
	ds_read_b128 v[156:159], v195 offset:3072
	s_add_i32 m0, s64, 0xc000
	ds_read_b128 v[160:163], v248
	ds_read_b128 v[164:167], v248 offset:1024
	ds_read_b128 v[168:171], v248 offset:2048
	ds_read_b128 v[172:175], v248 offset:3072
	ds_read_b128 v[176:179], v248 offset:4096
	ds_read_b128 v[180:183], v248 offset:5120
	ds_read_b128 v[184:187], v248 offset:6144
	ds_read_b128 v[188:191], v248 offset:7168
	global_load_lds_dwordx4 v206, s[82:83]
	s_add_i32 m0, s64, 0xe000
	s_nop 0
	global_load_lds_dwordx4 v204, s[82:83]
	s_waitcnt vmcnt(8)
	s_waitcnt lgkmcnt(0)
	s_barrier
	s_waitcnt lgkmcnt(0)
	v_mfma_f32_16x16x32_bf16 v[140:143], v[112:115], v[160:163], v[140:143]
	v_mfma_f32_16x16x32_bf16 v[132:135], v[128:131], v[160:163], v[132:135]
	v_mfma_f32_16x16x32_bf16 v[108:111], v[112:115], v[168:171], v[108:111]
	v_mfma_f32_16x16x32_bf16 v[104:107], v[128:131], v[168:171], v[104:107]
	v_mfma_f32_16x16x32_bf16 v[92:95], v[112:115], v[176:179], v[92:95]
	v_mfma_f32_16x16x32_bf16 v[88:91], v[128:131], v[176:179], v[88:91]
	v_mfma_f32_16x16x32_bf16 v[76:79], v[112:115], v[184:187], v[76:79]
	v_mfma_f32_16x16x32_bf16 v[72:75], v[128:131], v[184:187], v[72:75]
	v_mfma_f32_16x16x32_bf16 v[140:143], v[124:127], v[164:167], v[140:143]
	v_mfma_f32_16x16x32_bf16 v[132:135], v[136:139], v[164:167], v[132:135]
	v_mfma_f32_16x16x32_bf16 v[108:111], v[124:127], v[172:175], v[108:111]
	v_mfma_f32_16x16x32_bf16 v[104:107], v[136:139], v[172:175], v[104:107]
	v_mfma_f32_16x16x32_bf16 v[92:95], v[124:127], v[180:183], v[92:95]
	v_mfma_f32_16x16x32_bf16 v[88:91], v[136:139], v[180:183], v[88:91]
	v_mfma_f32_16x16x32_bf16 v[76:79], v[124:127], v[188:191], v[76:79]
	v_mfma_f32_16x16x32_bf16 v[72:75], v[136:139], v[188:191], v[72:75]
	v_mfma_f32_16x16x32_bf16 v[120:123], v[144:147], v[160:163], v[120:123]
	v_mfma_f32_16x16x32_bf16 v[116:119], v[152:155], v[160:163], v[116:119]
	v_mfma_f32_16x16x32_bf16 v[100:103], v[144:147], v[168:171], v[100:103]
	v_mfma_f32_16x16x32_bf16 v[96:99], v[152:155], v[168:171], v[96:99]
	v_mfma_f32_16x16x32_bf16 v[84:87], v[144:147], v[176:179], v[84:87]
	v_mfma_f32_16x16x32_bf16 v[80:83], v[152:155], v[176:179], v[80:83]
	v_mfma_f32_16x16x32_bf16 v[68:71], v[144:147], v[184:187], v[68:71]
	v_mfma_f32_16x16x32_bf16 v[64:67], v[152:155], v[184:187], v[64:67]
	v_mfma_f32_16x16x32_bf16 v[120:123], v[148:151], v[164:167], v[120:123]
	v_mfma_f32_16x16x32_bf16 v[116:119], v[156:159], v[164:167], v[116:119]
	v_mfma_f32_16x16x32_bf16 v[100:103], v[148:151], v[172:175], v[100:103]
	v_mfma_f32_16x16x32_bf16 v[96:99], v[156:159], v[172:175], v[96:99]
	v_mfma_f32_16x16x32_bf16 v[84:87], v[148:151], v[180:183], v[84:87]
	v_mfma_f32_16x16x32_bf16 v[80:83], v[156:159], v[180:183], v[80:83]
	v_mfma_f32_16x16x32_bf16 v[68:71], v[148:151], v[188:191], v[68:71]
	v_mfma_f32_16x16x32_bf16 v[64:67], v[156:159], v[188:191], v[64:67]
	s_barrier
; #define PG8_STAGE(bufoff, gbase, voff) do { _Pragma("unroll") for (int _i = 0; _i < 2; ++_i) \
;         __builtin_amdgcn_global_load_lds((const unsigned*)((const char*)(gbase) + (voff)[_i]), (PG8_LAS unsigned*)(lds + (bufoff) + ldsw + _i * 8192), 16, 0, 0); } while (0)
; #define PG8_LDA(dst, b, h) do { _Pragma("unroll") for (int m = 0; m < 4; ++m) _Pragma("unroll") for (int k = 0; k < 2; ++k) dst[m][k] = *(const PG8_LAS bf16x8*)(lds + PG8_SA(b, h) + aoff + m * 2048 + k * 1024); } while (0)
; #define PG8_LDB(dst, b, h) do { _Pragma("unroll") for (int n = 0; n < 2; ++n) _Pragma("unroll") for (int k = 0; k < 2; ++k) dst[n][k] = *(const PG8_LAS bf16x8*)(lds + PG8_SB(b, h) + boff + n * 2048 + k * 1024); } while (0)
; #define PG8_MMA(ai, bj, At, Bt) do { __builtin_amdgcn_s_setprio(1); _Pragma("unroll") for (int m = 0; m < 4; ++m) _Pragma("unroll") for (int n = 0; n < 2; ++n) _Pragma("unroll") for (int k = 0; k < 2; ++k) \
;         acc[ai][bj][m][n] = __builtin_amdgcn_mfma_f32_16x16x32_bf16(Bt[n][k], At[m][k], acc[ai][bj][m][n], 0, 0, 0); __builtin_amdgcn_s_setprio(0); } while (0)
; #define PG8_WAIT_V(n) asm volatile("s_waitcnt vmcnt(" #n ")" ::: "memory")
; #define PG8_WAIT_L(n) asm volatile("s_waitcnt lgkmcnt(" #n ")" ::: "memory")
; #define PG8_BAR __builtin_amdgcn_s_barrier()
; #define PG8_SCHED __builtin_amdgcn_sched_barrier(0)
; template <class Epi, class Sched, bool ALIGN_EPI = false, bool SP2 = false>
; __device__ __forceinline__ void gemm_phase(PG8_LAS unsigned char* lds, const Gemm g, const Sched& S, const Epi& E) {
;     ...
;             PG8_LDA(At, 0, 1); PG8_STAGE(PG8_SB(0, 0), b2, voffB); PG8_STAGE(PG8_SB(0, 1), b2 + hstepB, voffB); PG8_STAGE(PG8_SA(0, 0), a2, voffA);
;             PG8_WAIT_V(8); PG8_WAIT_L(0); PG8_BAR; PG8_MMA(1, 0, At, B0); PG8_MMA(1, 1, At, B1); PG8_BAR; PG8_SCHED;
;             PG8_LDB(B0, 1, 0); PG8_LDB(B1, 1, 1); PG8_SCHED; PG8_LDA(At, 1, 0); PG8_STAGE(PG8_SA(0, 1), a2 + hstepA, voffA);
	s_add_i32 s77, s77, s63
	v_lshl_add_u64 v[208:209], s[30:31], 0, v[192:193]
	s_mov_b32 m0, s77
	ds_read_b128 v[160:163], v248 offset:16384
	ds_read_b128 v[164:167], v248 offset:17408
	ds_read_b128 v[168:171], v248 offset:18432
	ds_read_b128 v[172:175], v248 offset:19456
	ds_read_b128 v[176:179], v248 offset:20480
	ds_read_b128 v[180:183], v248 offset:21504
	ds_read_b128 v[184:187], v248 offset:22528
	ds_read_b128 v[188:191], v248 offset:23552
	global_load_lds_dwordx4 v192, s[30:31]
	s_add_i32 m0, s77, 0x2000
	v_lshl_add_u64 v[210:211], s[30:31], 0, v[198:199]
	global_load_lds_dwordx4 v198, s[30:31]
	s_add_u32 s30, s30, s45
	s_addc_u32 s31, s31, 0
	s_add_i32 s3, s3, s63
	v_lshl_add_u64 v[212:213], s[30:31], 0, v[192:193]
	s_mov_b32 m0, s3
	v_lshl_add_u64 v[214:215], s[30:31], 0, v[198:199]
	global_load_lds_dwordx4 v192, s[30:31]
	s_add_i32 m0, s3, 0x2000
	s_nop 0
	global_load_lds_dwordx4 v198, s[30:31]
	s_mov_b32 m0, s64
	s_nop 0
	global_load_lds_dwordx4 v202, s[84:85]
	s_mov_b32 m0, s65
	s_nop 0
	global_load_lds_dwordx4 v200, s[84:85]
	s_waitcnt vmcnt(8)
	s_waitcnt lgkmcnt(0)
	s_barrier
	s_waitcnt lgkmcnt(0)
	v_mfma_f32_16x16x32_bf16 v[60:63], v[112:115], v[160:163], v[60:63]
	v_mfma_f32_16x16x32_bf16 v[56:59], v[128:131], v[160:163], v[56:59]
	v_mfma_f32_16x16x32_bf16 v[44:47], v[112:115], v[168:171], v[44:47]
	v_mfma_f32_16x16x32_bf16 v[40:43], v[128:131], v[168:171], v[40:43]
	v_mfma_f32_16x16x32_bf16 v[28:31], v[112:115], v[176:179], v[28:31]
	v_mfma_f32_16x16x32_bf16 v[24:27], v[128:131], v[176:179], v[24:27]
	v_mfma_f32_16x16x32_bf16 v[12:15], v[112:115], v[184:187], v[12:15]
	v_mfma_f32_16x16x32_bf16 v[8:11], v[128:131], v[184:187], v[8:11]
	v_mfma_f32_16x16x32_bf16 v[60:63], v[124:127], v[164:167], v[60:63]
	v_mfma_f32_16x16x32_bf16 v[56:59], v[136:139], v[164:167], v[56:59]
	v_mfma_f32_16x16x32_bf16 v[44:47], v[124:127], v[172:175], v[44:47]
	v_mfma_f32_16x16x32_bf16 v[40:43], v[136:139], v[172:175], v[40:43]
	v_mfma_f32_16x16x32_bf16 v[28:31], v[124:127], v[180:183], v[28:31]
	v_mfma_f32_16x16x32_bf16 v[24:27], v[136:139], v[180:183], v[24:27]
	v_mfma_f32_16x16x32_bf16 v[12:15], v[124:127], v[188:191], v[12:15]
	v_mfma_f32_16x16x32_bf16 v[8:11], v[136:139], v[188:191], v[8:11]
	v_mfma_f32_16x16x32_bf16 v[52:55], v[144:147], v[160:163], v[52:55]
	v_mfma_f32_16x16x32_bf16 v[48:51], v[152:155], v[160:163], v[48:51]
	v_mfma_f32_16x16x32_bf16 v[36:39], v[144:147], v[168:171], v[36:39]
	v_mfma_f32_16x16x32_bf16 v[32:35], v[152:155], v[168:171], v[32:35]
	v_mfma_f32_16x16x32_bf16 v[20:23], v[144:147], v[176:179], v[20:23]
	v_mfma_f32_16x16x32_bf16 v[16:19], v[152:155], v[176:179], v[16:19]
	v_mfma_f32_16x16x32_bf16 v[4:7], v[144:147], v[184:187], v[4:7]
	v_mfma_f32_16x16x32_bf16 v[0:3], v[152:155], v[184:187], v[0:3]
	v_mfma_f32_16x16x32_bf16 v[52:55], v[148:151], v[164:167], v[52:55]
	v_mfma_f32_16x16x32_bf16 v[48:51], v[156:159], v[164:167], v[48:51]
	v_mfma_f32_16x16x32_bf16 v[36:39], v[148:151], v[172:175], v[36:39]
	v_mfma_f32_16x16x32_bf16 v[32:35], v[156:159], v[172:175], v[32:35]
	v_mfma_f32_16x16x32_bf16 v[20:23], v[148:151], v[180:183], v[20:23]
	v_mfma_f32_16x16x32_bf16 v[16:19], v[156:159], v[180:183], v[16:19]
	v_mfma_f32_16x16x32_bf16 v[4:7], v[148:151], v[188:191], v[4:7]
	v_mfma_f32_16x16x32_bf16 v[0:3], v[156:159], v[188:191], v[0:3]
	s_barrier
	s_add_i32 s3, 0, 0x18000
	s_add_i32 s77, 0, 0x1c000
	ds_read_b128 v[112:115], v196
	ds_read_b128 v[124:127], v196 offset:1024
	ds_read_b128 v[128:131], v196 offset:2048
	ds_read_b128 v[136:139], v196 offset:3072
	ds_read_b128 v[144:147], v197
	ds_read_b128 v[148:151], v197 offset:1024
	ds_read_b128 v[152:155], v197 offset:2048
	ds_read_b128 v[156:159], v197 offset:3072
	s_add_u32 s30, s84, s10
	s_addc_u32 s31, s85, 0
	s_mov_b32 m0, s80
	ds_read_b128 v[160:163], v248 offset:32768
	ds_read_b128 v[164:167], v248 offset:33792
	ds_read_b128 v[168:171], v248 offset:34816
	ds_read_b128 v[172:175], v248 offset:35840
	ds_read_b128 v[176:179], v248 offset:36864
	ds_read_b128 v[180:183], v248 offset:37888
	ds_read_b128 v[184:187], v248 offset:38912
	ds_read_b128 v[188:191], v248 offset:39936
	global_load_lds_dwordx4 v202, s[30:31]
	s_mov_b32 m0, s86
	s_nop 0
	global_load_lds_dwordx4 v200, s[30:31]
	s_waitcnt vmcnt(8)
	s_waitcnt lgkmcnt(0)
	s_barrier
; #define PG8_STAGE(bufoff, gbase, voff) do { _Pragma("unroll") for (int _i = 0; _i < 2; ++_i) \
;         __builtin_amdgcn_global_load_lds((const unsigned*)((const char*)(gbase) + (voff)[_i]), (PG8_LAS unsigned*)(lds + (bufoff) + ldsw + _i * 8192), 16, 0, 0); } while (0)
; #define PG8_LDA(dst, b, h) do { _Pragma("unroll") for (int m = 0; m < 4; ++m) _Pragma("unroll") for (int k = 0; k < 2; ++k) dst[m][k] = *(const PG8_LAS bf16x8*)(lds + PG8_SA(b, h) + aoff + m * 2048 + k * 1024); } while (0)
; #define PG8_MMA(ai, bj, At, Bt) do { __builtin_amdgcn_s_setprio(1); _Pragma("unroll") for (int m = 0; m < 4; ++m) _Pragma("unroll") for (int n = 0; n < 2; ++n) _Pragma("unroll") for (int k = 0; k < 2; ++k) \
;         acc[ai][bj][m][n] = __builtin_amdgcn_mfma_f32_16x16x32_bf16(Bt[n][k], At[m][k], acc[ai][bj][m][n], 0, 0, 0); __builtin_amdgcn_s_setprio(0); } while (0)
; #define PG8_WAIT_V(n) asm volatile("s_waitcnt vmcnt(" #n ")" ::: "memory")
; #define PG8_WAIT_L(n) asm volatile("s_waitcnt lgkmcnt(" #n ")" ::: "memory")
; #define PG8_BAR __builtin_amdgcn_s_barrier()
; #define PG8_SCHED __builtin_amdgcn_sched_barrier(0)
; template <class Epi, class Sched, bool ALIGN_EPI = false, bool SP2 = false>
; __device__ __forceinline__ void gemm_phase(PG8_LAS unsigned char* lds, const Gemm g, const Sched& S, const Epi& E) {
;     ...
;             PG8_WAIT_V(8); PG8_WAIT_L(0); PG8_BAR; PG8_MMA(0, 0, At, B0); PG8_MMA(0, 1, At, B1); PG8_BAR; PG8_SCHED;
;             PG8_LDA(At, 1, 1); PG8_STAGE(PG8_SB(1, 0), b3, voffB); PG8_STAGE(PG8_SB(1, 1), b3 + hstepB, voffB); PG8_STAGE(PG8_SA(1, 0), a3, voffA);
;             PG8_WAIT_V(8); PG8_WAIT_L(0); PG8_BAR; PG8_MMA(1, 0, At, B0); PG8_MMA(1, 1, At, B1); PG8_BAR; PG8_SCHED;
;     ...
;         if constexpr (ALIGN_EPI) { if (wr == 0) PG8_BAR; }
	s_waitcnt lgkmcnt(0)
	v_mfma_f32_16x16x32_bf16 v[140:143], v[112:115], v[160:163], v[140:143]
	v_mfma_f32_16x16x32_bf16 v[132:135], v[128:131], v[160:163], v[132:135]
	v_mfma_f32_16x16x32_bf16 v[108:111], v[112:115], v[168:171], v[108:111]
	v_mfma_f32_16x16x32_bf16 v[104:107], v[128:131], v[168:171], v[104:107]
	v_mfma_f32_16x16x32_bf16 v[92:95], v[112:115], v[176:179], v[92:95]
	v_mfma_f32_16x16x32_bf16 v[88:91], v[128:131], v[176:179], v[88:91]
	v_mfma_f32_16x16x32_bf16 v[76:79], v[112:115], v[184:187], v[76:79]
	v_mfma_f32_16x16x32_bf16 v[72:75], v[128:131], v[184:187], v[72:75]
	v_mfma_f32_16x16x32_bf16 v[140:143], v[124:127], v[164:167], v[140:143]
	v_mfma_f32_16x16x32_bf16 v[132:135], v[136:139], v[164:167], v[132:135]
	v_mfma_f32_16x16x32_bf16 v[108:111], v[124:127], v[172:175], v[108:111]
	v_mfma_f32_16x16x32_bf16 v[104:107], v[136:139], v[172:175], v[104:107]
	v_mfma_f32_16x16x32_bf16 v[92:95], v[124:127], v[180:183], v[92:95]
	v_mfma_f32_16x16x32_bf16 v[88:91], v[136:139], v[180:183], v[88:91]
	v_mfma_f32_16x16x32_bf16 v[76:79], v[124:127], v[188:191], v[76:79]
	v_mfma_f32_16x16x32_bf16 v[72:75], v[136:139], v[188:191], v[72:75]
	v_mfma_f32_16x16x32_bf16 v[120:123], v[144:147], v[160:163], v[120:123]
	v_mfma_f32_16x16x32_bf16 v[116:119], v[152:155], v[160:163], v[116:119]
	v_mfma_f32_16x16x32_bf16 v[100:103], v[144:147], v[168:171], v[100:103]
	v_mfma_f32_16x16x32_bf16 v[96:99], v[152:155], v[168:171], v[96:99]
	v_mfma_f32_16x16x32_bf16 v[84:87], v[144:147], v[176:179], v[84:87]
	v_mfma_f32_16x16x32_bf16 v[80:83], v[152:155], v[176:179], v[80:83]
	v_mfma_f32_16x16x32_bf16 v[68:71], v[144:147], v[184:187], v[68:71]
	v_mfma_f32_16x16x32_bf16 v[64:67], v[152:155], v[184:187], v[64:67]
	v_mfma_f32_16x16x32_bf16 v[120:123], v[148:151], v[164:167], v[120:123]
	v_mfma_f32_16x16x32_bf16 v[116:119], v[156:159], v[164:167], v[116:119]
	v_mfma_f32_16x16x32_bf16 v[100:103], v[148:151], v[172:175], v[100:103]
	v_mfma_f32_16x16x32_bf16 v[96:99], v[156:159], v[172:175], v[96:99]
	v_mfma_f32_16x16x32_bf16 v[84:87], v[148:151], v[180:183], v[84:87]
	v_mfma_f32_16x16x32_bf16 v[80:83], v[156:159], v[180:183], v[80:83]
	v_mfma_f32_16x16x32_bf16 v[68:71], v[148:151], v[188:191], v[68:71]
	v_mfma_f32_16x16x32_bf16 v[64:67], v[156:159], v[188:191], v[64:67]
	s_barrier
	s_add_i32 s3, s3, s63
	v_lshl_add_u64 v[208:209], v[208:209], 0, s[36:37]
	s_mov_b32 m0, s3
	ds_read_b128 v[160:163], v248 offset:49152
	ds_read_b128 v[164:167], v248 offset:50176
	ds_read_b128 v[168:171], v248 offset:51200
	ds_read_b128 v[172:175], v248 offset:52224
	ds_read_b128 v[176:179], v248 offset:53248
	ds_read_b128 v[180:183], v248 offset:54272
	ds_read_b128 v[184:187], v248 offset:55296
	ds_read_b128 v[188:191], v248 offset:56320
	global_load_lds_dwordx4 v[208:209], off
	v_lshl_add_u64 v[208:209], v[210:211], 0, s[36:37]
	s_add_i32 m0, s3, 0x2000
	s_add_i32 s3, s77, s63
	global_load_lds_dwordx4 v[208:209], off
	v_lshl_add_u64 v[208:209], v[212:213], 0, s[36:37]
	s_mov_b32 m0, s3
	s_nop 0
	global_load_lds_dwordx4 v[208:209], off
	v_lshl_add_u64 v[208:209], v[214:215], 0, s[36:37]
	s_add_i32 m0, s3, 0x2000
	s_nop 0
	global_load_lds_dwordx4 v[208:209], off
	s_add_i32 m0, s91, 0xffffff80
	s_nop 0
	global_load_lds_dwordx4 v202, s[84:85] offset:128
	s_add_i32 m0, s92, 0xffffff80
	s_nop 0
	global_load_lds_dwordx4 v200, s[84:85] offset:128
	s_waitcnt vmcnt(8)
	s_waitcnt lgkmcnt(0)
	s_barrier
	s_waitcnt lgkmcnt(0)
	v_mfma_f32_16x16x32_bf16 v[60:63], v[112:115], v[160:163], v[60:63]
	v_mfma_f32_16x16x32_bf16 v[56:59], v[128:131], v[160:163], v[56:59]
	v_mfma_f32_16x16x32_bf16 v[44:47], v[112:115], v[168:171], v[44:47]
	v_mfma_f32_16x16x32_bf16 v[40:43], v[128:131], v[168:171], v[40:43]
	v_mfma_f32_16x16x32_bf16 v[28:31], v[112:115], v[176:179], v[28:31]
	v_mfma_f32_16x16x32_bf16 v[24:27], v[128:131], v[176:179], v[24:27]
	v_mfma_f32_16x16x32_bf16 v[12:15], v[112:115], v[184:187], v[12:15]
	v_mfma_f32_16x16x32_bf16 v[8:11], v[128:131], v[184:187], v[8:11]
	v_mfma_f32_16x16x32_bf16 v[60:63], v[124:127], v[164:167], v[60:63]
	v_mfma_f32_16x16x32_bf16 v[56:59], v[136:139], v[164:167], v[56:59]
	v_mfma_f32_16x16x32_bf16 v[44:47], v[124:127], v[172:175], v[44:47]
	v_mfma_f32_16x16x32_bf16 v[40:43], v[136:139], v[172:175], v[40:43]
	v_mfma_f32_16x16x32_bf16 v[28:31], v[124:127], v[180:183], v[28:31]
	v_mfma_f32_16x16x32_bf16 v[24:27], v[136:139], v[180:183], v[24:27]
	v_mfma_f32_16x16x32_bf16 v[12:15], v[124:127], v[188:191], v[12:15]
	v_mfma_f32_16x16x32_bf16 v[8:11], v[136:139], v[188:191], v[8:11]
	v_mfma_f32_16x16x32_bf16 v[52:55], v[144:147], v[160:163], v[52:55]
	v_mfma_f32_16x16x32_bf16 v[48:51], v[152:155], v[160:163], v[48:51]
	v_mfma_f32_16x16x32_bf16 v[36:39], v[144:147], v[168:171], v[36:39]
	v_mfma_f32_16x16x32_bf16 v[32:35], v[152:155], v[168:171], v[32:35]
	v_mfma_f32_16x16x32_bf16 v[20:23], v[144:147], v[176:179], v[20:23]
	v_mfma_f32_16x16x32_bf16 v[16:19], v[152:155], v[176:179], v[16:19]
	v_mfma_f32_16x16x32_bf16 v[4:7], v[144:147], v[184:187], v[4:7]
	v_mfma_f32_16x16x32_bf16 v[0:3], v[152:155], v[184:187], v[0:3]
	v_mfma_f32_16x16x32_bf16 v[52:55], v[148:151], v[164:167], v[52:55]
	v_mfma_f32_16x16x32_bf16 v[48:51], v[156:159], v[164:167], v[48:51]
	v_mfma_f32_16x16x32_bf16 v[36:39], v[148:151], v[172:175], v[36:39]
	v_mfma_f32_16x16x32_bf16 v[32:35], v[156:159], v[172:175], v[32:35]
	v_mfma_f32_16x16x32_bf16 v[20:23], v[148:151], v[180:183], v[20:23]
	v_mfma_f32_16x16x32_bf16 v[16:19], v[156:159], v[180:183], v[16:19]
	v_mfma_f32_16x16x32_bf16 v[4:7], v[148:151], v[188:191], v[4:7]
	v_mfma_f32_16x16x32_bf16 v[0:3], v[156:159], v[188:191], v[0:3]
	s_barrier
	s_add_u32 vcc_lo, vcc_lo, 0x100
	s_addc_u32 vcc_hi, vcc_hi, 0
	s_add_u32 s82, s82, 0x100
	s_addc_u32 s83, s83, 0
	s_cmp_ge_u32 s2, s87
	s_mov_b32 s84, s2
	s_cbranch_scc0 .LBB0_724
	s_and_b64 vcc, exec, s[16:17]
	s_cbranch_vccz .LBB0_727
	s_barrier

; #define PG8_STAGE(bufoff, gbase, voff) do { _Pragma("unroll") for (int _i = 0; _i < 2; ++_i) \
;         __builtin_amdgcn_global_load_lds((const unsigned*)((const char*)(gbase) + (voff)[_i]), (PG8_LAS unsigned*)(lds + (bufoff) + ldsw + _i * 8192), 16, 0, 0); } while (0)
; #define PG8_LDA(dst, b, h) do { _Pragma("unroll") for (int m = 0; m < 4; ++m) _Pragma("unroll") for (int k = 0; k < 2; ++k) dst[m][k] = *(const PG8_LAS bf16x8*)(lds + PG8_SA(b, h) + aoff + m * 2048 + k * 1024); } while (0)
; #define PG8_LDB(dst, b, h) do { _Pragma("unroll") for (int n = 0; n < 2; ++n) _Pragma("unroll") for (int k = 0; k < 2; ++k) dst[n][k] = *(const PG8_LAS bf16x8*)(lds + PG8_SB(b, h) + boff + n * 2048 + k * 1024); } while (0)
; #define PG8_WAIT_V(n) asm volatile("s_waitcnt vmcnt(" #n ")" ::: "memory")
; #define PG8_WAIT_L(n) asm volatile("s_waitcnt lgkmcnt(" #n ")" ::: "memory")
; #define PG8_BAR __builtin_amdgcn_s_barrier()
; template <class Epi, class Sched, bool ALIGN_EPI = false, bool SP2 = false>
; __device__ __forceinline__ void gemm_phase(PG8_LAS unsigned char* lds, const Gemm g, const Sched& S, const Epi& E) {
;     ...
;         const bool has_next = S.next(ui + 1, nxt);
;         const char* nA = has_next ? (const char*)g.A + (size_t)nxt.pm * tstepA : cA; const char* nB = has_next ? (const char*)g.Bt + (size_t)nxt.pn * tstepB : cB;
;         for (int t = 0; t < nt; t += 2) {
;             const bool last = (t == nt - 2);
;             const char* a1 = cA + (size_t)(t + 1) * kstep;
;             const char* a2 = last ? nA : cA + (size_t)(t + 2) * kstep; const char* b2 = last ? nB : cB + (size_t)(t + 2) * kstep;
;             const char* a3 = a2 + kstep; const char* b3 = b2 + kstep;
;             if (last && has_next) S.a_ready(nxt);
;             if constexpr (SP2) {
;             PG8_LDB(B0, 0, 0); PG8_LDB(B1, 0, 1); PG8_SCHED; PG8_LDA(At, 0, 0); PG8_STAGE(PG8_SA(1, 1), a1 + hstepA, voffA);
;             PG8_WAIT_V(8); PG8_WAIT_L(0); PG8_BAR; PG8_MMA(0, 0, At, B0); PG8_MMA(0, 1, At, B1); PG8_BAR; PG8_SCHED;
;     ...
; #pragma unroll
;         for (int a = 0; a < 2; ++a)
; #pragma unroll
;             for (int b = 0; b < 2; ++b)
; #pragma unroll
;                 for (int m = 0; m < 4; ++m)
; #pragma unroll
;                     for (int n = 0; n < 2; ++n) acc[a][b][m][n] = (f32x4){0.f, 0.f, 0.f, 0.f};
;         cur = nxt; cA = nA; cB = nB; ++ui;
.LBB0_765:
	s_add_u32 s93, s82, 0x100
	v_mov_b32_e32 v0, 0
	s_addc_u32 s94, s83, 0
	s_mov_b32 s82, 0
	v_mov_b32_e32 v1, v0
	v_mov_b32_e32 v2, v0
	v_mov_b32_e32 v3, v0
	v_mov_b32_e32 v4, v0
	v_mov_b32_e32 v5, v0
	v_mov_b32_e32 v6, v0
	v_mov_b32_e32 v7, v0
	v_mov_b32_e32 v12, v0
	v_mov_b32_e32 v13, v0
	v_mov_b32_e32 v14, v0
	v_mov_b32_e32 v15, v0
	v_mov_b32_e32 v20, v0
	v_mov_b32_e32 v21, v0
	v_mov_b32_e32 v22, v0
	v_mov_b32_e32 v23, v0
	v_mov_b32_e32 v28, v0
	v_mov_b32_e32 v29, v0
	v_mov_b32_e32 v30, v0
	v_mov_b32_e32 v31, v0
	v_mov_b32_e32 v36, v0
	v_mov_b32_e32 v37, v0
	v_mov_b32_e32 v38, v0
	v_mov_b32_e32 v39, v0
	v_mov_b32_e32 v44, v0
	v_mov_b32_e32 v45, v0
	v_mov_b32_e32 v46, v0
	v_mov_b32_e32 v47, v0
	v_mov_b32_e32 v52, v0
	v_mov_b32_e32 v53, v0
	v_mov_b32_e32 v54, v0
	v_mov_b32_e32 v55, v0
	v_mov_b32_e32 v8, v0
	v_mov_b32_e32 v9, v0
	v_mov_b32_e32 v10, v0
	v_mov_b32_e32 v11, v0
	v_mov_b32_e32 v16, v0
	v_mov_b32_e32 v17, v0
	v_mov_b32_e32 v18, v0
	v_mov_b32_e32 v19, v0
	v_mov_b32_e32 v24, v0
	v_mov_b32_e32 v25, v0
	v_mov_b32_e32 v26, v0
	v_mov_b32_e32 v27, v0
	v_mov_b32_e32 v32, v0
	v_mov_b32_e32 v33, v0
	v_mov_b32_e32 v34, v0
	v_mov_b32_e32 v35, v0
	v_mov_b32_e32 v40, v0
	v_mov_b32_e32 v41, v0
	v_mov_b32_e32 v42, v0
	v_mov_b32_e32 v43, v0
	v_mov_b32_e32 v48, v0
	v_mov_b32_e32 v49, v0
	v_mov_b32_e32 v50, v0
	v_mov_b32_e32 v51, v0
	v_mov_b32_e32 v56, v0
	v_mov_b32_e32 v57, v0
	v_mov_b32_e32 v58, v0
	v_mov_b32_e32 v59, v0
	v_mov_b32_e32 v60, v0
	v_mov_b32_e32 v61, v0
	v_mov_b32_e32 v62, v0
	v_mov_b32_e32 v63, v0
	s_waitcnt vmcnt(0)
	v_mov_b32_e32 v64, v0
	v_mov_b32_e32 v65, v0
	v_mov_b32_e32 v66, v0
	v_mov_b32_e32 v67, v0
	v_mov_b32_e32 v68, v0
	v_mov_b32_e32 v69, v0
	v_mov_b32_e32 v70, v0
	v_mov_b32_e32 v71, v0
	v_mov_b32_e32 v76, v0
	v_mov_b32_e32 v77, v0
	v_mov_b32_e32 v78, v0
	v_mov_b32_e32 v79, v0
	v_mov_b32_e32 v84, v0
	v_mov_b32_e32 v85, v0
	v_mov_b32_e32 v86, v0
	v_mov_b32_e32 v87, v0
	v_mov_b32_e32 v92, v0
	v_mov_b32_e32 v93, v0
	v_mov_b32_e32 v94, v0
	v_mov_b32_e32 v95, v0
	v_mov_b32_e32 v100, v0
	v_mov_b32_e32 v101, v0
	v_mov_b32_e32 v102, v0
	v_mov_b32_e32 v103, v0
	v_mov_b32_e32 v108, v0
	v_mov_b32_e32 v109, v0
	v_mov_b32_e32 v110, v0
	v_mov_b32_e32 v111, v0
	v_mov_b32_e32 v116, v0
	v_mov_b32_e32 v117, v0
	v_mov_b32_e32 v118, v0
	v_mov_b32_e32 v119, v0
	v_mov_b32_e32 v72, v0
	v_mov_b32_e32 v73, v0
	v_mov_b32_e32 v74, v0
	v_mov_b32_e32 v75, v0
	v_mov_b32_e32 v80, v0
	v_mov_b32_e32 v81, v0
	v_mov_b32_e32 v82, v0
	v_mov_b32_e32 v83, v0
	v_mov_b32_e32 v88, v0
	v_mov_b32_e32 v89, v0
	v_mov_b32_e32 v90, v0
	v_mov_b32_e32 v91, v0
	v_mov_b32_e32 v96, v0
	v_mov_b32_e32 v97, v0
	v_mov_b32_e32 v98, v0
	v_mov_b32_e32 v99, v0
	v_mov_b32_e32 v104, v0
	v_mov_b32_e32 v105, v0
	v_mov_b32_e32 v106, v0
	v_mov_b32_e32 v107, v0
	v_mov_b32_e32 v112, v0
	v_mov_b32_e32 v113, v0
	v_mov_b32_e32 v114, v0
	v_mov_b32_e32 v115, v0
	v_mov_b32_e32 v120, v0
	v_mov_b32_e32 v121, v0
	v_mov_b32_e32 v122, v0
	v_mov_b32_e32 v123, v0
	v_mov_b32_e32 v124, v0
	v_mov_b32_e32 v125, v0
	v_mov_b32_e32 v126, v0
	v_mov_b32_e32 v127, v0
	v_add_u32_e32 v194, 0x10000, v222
	v_add_u32_e32 v195, 0x14000, v222
	v_add_u32_e32 v196, 0x18000, v222
	v_add_u32_e32 v197, 0x1c000, v222
.LBB0_766:
	s_add_i32 s2, s82, 2
	s_add_u32 s4, s66, 0x100
	s_addc_u32 s5, s67, 0
	s_add_i32 s3, 0, 0x10000
	s_cmp_eq_u32 s88, s82
	s_cselect_b32 s83, s15, s5
	s_cselect_b32 s82, s14, s4
	s_cselect_b32 s97, s17, s94
	s_cselect_b32 s96, s16, s93
	s_add_i32 s30, 0, 0x14000
	ds_read_b128 v[128:131], v194
	ds_read_b128 v[132:135], v194 offset:1024
	ds_read_b128 v[136:139], v194 offset:2048
	ds_read_b128 v[140:143], v194 offset:3072
	ds_read_b128 v[144:147], v195
	ds_read_b128 v[148:151], v195 offset:1024
	ds_read_b128 v[152:155], v195 offset:2048
	ds_read_b128 v[156:159], v195 offset:3072
	s_add_i32 m0, s62, 0xc000
	ds_read_b128 v[160:163], v223
	ds_read_b128 v[164:167], v223 offset:1024
	ds_read_b128 v[168:171], v223 offset:2048
	ds_read_b128 v[172:175], v223 offset:3072
	ds_read_b128 v[176:179], v223 offset:4096
	ds_read_b128 v[180:183], v223 offset:5120
	ds_read_b128 v[184:187], v223 offset:6144
	ds_read_b128 v[188:191], v223 offset:7168
	global_load_lds_dwordx4 v206, s[66:67]
	s_add_i32 m0, s62, 0xe000
	s_nop 0
	global_load_lds_dwordx4 v204, s[66:67]
	s_waitcnt vmcnt(8)
	s_waitcnt lgkmcnt(0)
	s_barrier
	s_waitcnt lgkmcnt(0)
	v_mfma_f32_16x16x32_bf16 v[124:127], v[128:131], v[160:163], v[124:127]
	v_mfma_f32_16x16x32_bf16 v[120:123], v[136:139], v[160:163], v[120:123]
	v_mfma_f32_16x16x32_bf16 v[112:115], v[128:131], v[168:171], v[112:115]
	v_mfma_f32_16x16x32_bf16 v[104:107], v[136:139], v[168:171], v[104:107]
	v_mfma_f32_16x16x32_bf16 v[96:99], v[128:131], v[176:179], v[96:99]
	v_mfma_f32_16x16x32_bf16 v[88:91], v[136:139], v[176:179], v[88:91]
	v_mfma_f32_16x16x32_bf16 v[80:83], v[128:131], v[184:187], v[80:83]
	v_mfma_f32_16x16x32_bf16 v[72:75], v[136:139], v[184:187], v[72:75]
	v_mfma_f32_16x16x32_bf16 v[124:127], v[132:135], v[164:167], v[124:127]
	v_mfma_f32_16x16x32_bf16 v[120:123], v[140:143], v[164:167], v[120:123]
	v_mfma_f32_16x16x32_bf16 v[112:115], v[132:135], v[172:175], v[112:115]
	v_mfma_f32_16x16x32_bf16 v[104:107], v[140:143], v[172:175], v[104:107]
	v_mfma_f32_16x16x32_bf16 v[96:99], v[132:135], v[180:183], v[96:99]
	v_mfma_f32_16x16x32_bf16 v[88:91], v[140:143], v[180:183], v[88:91]
	v_mfma_f32_16x16x32_bf16 v[80:83], v[132:135], v[188:191], v[80:83]
	v_mfma_f32_16x16x32_bf16 v[72:75], v[140:143], v[188:191], v[72:75]
	v_mfma_f32_16x16x32_bf16 v[116:119], v[144:147], v[160:163], v[116:119]
	v_mfma_f32_16x16x32_bf16 v[108:111], v[152:155], v[160:163], v[108:111]
	v_mfma_f32_16x16x32_bf16 v[100:103], v[144:147], v[168:171], v[100:103]
	v_mfma_f32_16x16x32_bf16 v[92:95], v[152:155], v[168:171], v[92:95]
	v_mfma_f32_16x16x32_bf16 v[84:87], v[144:147], v[176:179], v[84:87]
	v_mfma_f32_16x16x32_bf16 v[76:79], v[152:155], v[176:179], v[76:79]
	v_mfma_f32_16x16x32_bf16 v[68:71], v[144:147], v[184:187], v[68:71]
	v_mfma_f32_16x16x32_bf16 v[64:67], v[152:155], v[184:187], v[64:67]
	v_mfma_f32_16x16x32_bf16 v[116:119], v[148:151], v[164:167], v[116:119]
	v_mfma_f32_16x16x32_bf16 v[108:111], v[156:159], v[164:167], v[108:111]
	v_mfma_f32_16x16x32_bf16 v[100:103], v[148:151], v[172:175], v[100:103]
	v_mfma_f32_16x16x32_bf16 v[92:95], v[156:159], v[172:175], v[92:95]
	v_mfma_f32_16x16x32_bf16 v[84:87], v[148:151], v[180:183], v[84:87]
	v_mfma_f32_16x16x32_bf16 v[76:79], v[156:159], v[180:183], v[76:79]
	v_mfma_f32_16x16x32_bf16 v[68:71], v[148:151], v[188:191], v[68:71]
	v_mfma_f32_16x16x32_bf16 v[64:67], v[156:159], v[188:191], v[64:67]
	s_barrier
; #define PG8_STAGE(bufoff, gbase, voff) do { _Pragma("unroll") for (int _i = 0; _i < 2; ++_i) \
;         __builtin_amdgcn_global_load_lds((const unsigned*)((const char*)(gbase) + (voff)[_i]), (PG8_LAS unsigned*)(lds + (bufoff) + ldsw + _i * 8192), 16, 0, 0); } while (0)
; #define PG8_LDA(dst, b, h) do { _Pragma("unroll") for (int m = 0; m < 4; ++m) _Pragma("unroll") for (int k = 0; k < 2; ++k) dst[m][k] = *(const PG8_LAS bf16x8*)(lds + PG8_SA(b, h) + aoff + m * 2048 + k * 1024); } while (0)
; #define PG8_LDB(dst, b, h) do { _Pragma("unroll") for (int n = 0; n < 2; ++n) _Pragma("unroll") for (int k = 0; k < 2; ++k) dst[n][k] = *(const PG8_LAS bf16x8*)(lds + PG8_SB(b, h) + boff + n * 2048 + k * 1024); } while (0)
; #define PG8_MMA(ai, bj, At, Bt) do { __builtin_amdgcn_s_setprio(1); _Pragma("unroll") for (int m = 0; m < 4; ++m) _Pragma("unroll") for (int n = 0; n < 2; ++n) _Pragma("unroll") for (int k = 0; k < 2; ++k) \
;         acc[ai][bj][m][n] = __builtin_amdgcn_mfma_f32_16x16x32_bf16(Bt[n][k], At[m][k], acc[ai][bj][m][n], 0, 0, 0); __builtin_amdgcn_s_setprio(0); } while (0)
; #define PG8_WAIT_V(n) asm volatile("s_waitcnt vmcnt(" #n ")" ::: "memory")
; #define PG8_WAIT_L(n) asm volatile("s_waitcnt lgkmcnt(" #n ")" ::: "memory")
; #define PG8_BAR __builtin_amdgcn_s_barrier()
; #define PG8_SCHED __builtin_amdgcn_sched_barrier(0)
; template <class Epi, class Sched, bool ALIGN_EPI = false, bool SP2 = false>
; __device__ __forceinline__ void gemm_phase(PG8_LAS unsigned char* lds, const Gemm g, const Sched& S, const Epi& E) {
;     ...
;             PG8_LDA(At, 0, 1); PG8_STAGE(PG8_SB(0, 0), b2, voffB); PG8_STAGE(PG8_SB(0, 1), b2 + hstepB, voffB); PG8_STAGE(PG8_SA(0, 0), a2, voffA);
;             PG8_WAIT_V(8); PG8_WAIT_L(0); PG8_BAR; PG8_MMA(1, 0, At, B0); PG8_MMA(1, 1, At, B1); PG8_BAR; PG8_SCHED;
;             PG8_LDB(B0, 1, 0); PG8_LDB(B1, 1, 1); PG8_SCHED; PG8_LDA(At, 1, 0); PG8_STAGE(PG8_SA(0, 1), a2 + hstepA, voffA);
	s_add_i32 s3, s3, s49
	s_mov_b32 m0, s3
	ds_read_b128 v[160:163], v223 offset:16384
	ds_read_b128 v[164:167], v223 offset:17408
	ds_read_b128 v[168:171], v223 offset:18432
	ds_read_b128 v[172:175], v223 offset:19456
	ds_read_b128 v[176:179], v223 offset:20480
	ds_read_b128 v[180:183], v223 offset:21504
	ds_read_b128 v[184:187], v223 offset:22528
	ds_read_b128 v[188:191], v223 offset:23552
	global_load_lds_dwordx4 v192, s[96:97]
	s_add_i32 m0, s3, 0x2000
	s_add_u32 s66, s96, s34
	s_addc_u32 s67, s97, 0
	s_add_i32 s3, s30, s49
	global_load_lds_dwordx4 v198, s[96:97]
	v_lshl_add_u64 v[212:213], s[66:67], 0, v[192:193]
	s_mov_b32 m0, s3
	v_lshl_add_u64 v[214:215], s[66:67], 0, v[198:199]
	global_load_lds_dwordx4 v192, s[66:67]
	s_add_i32 m0, s3, 0x2000
	s_nop 0
	global_load_lds_dwordx4 v198, s[66:67]
	s_mov_b32 m0, s62
	s_nop 0
	global_load_lds_dwordx4 v202, s[82:83]
	s_mov_b32 m0, s63
	s_nop 0
	global_load_lds_dwordx4 v200, s[82:83]
	s_waitcnt vmcnt(8)
	s_waitcnt lgkmcnt(0)
	s_barrier
	s_waitcnt lgkmcnt(0)
	v_mfma_f32_16x16x32_bf16 v[60:63], v[128:131], v[160:163], v[60:63]
	v_mfma_f32_16x16x32_bf16 v[56:59], v[136:139], v[160:163], v[56:59]
	v_mfma_f32_16x16x32_bf16 v[48:51], v[128:131], v[168:171], v[48:51]
	v_mfma_f32_16x16x32_bf16 v[40:43], v[136:139], v[168:171], v[40:43]
	v_mfma_f32_16x16x32_bf16 v[32:35], v[128:131], v[176:179], v[32:35]
	v_mfma_f32_16x16x32_bf16 v[24:27], v[136:139], v[176:179], v[24:27]
	v_mfma_f32_16x16x32_bf16 v[16:19], v[128:131], v[184:187], v[16:19]
	v_mfma_f32_16x16x32_bf16 v[8:11], v[136:139], v[184:187], v[8:11]
	v_mfma_f32_16x16x32_bf16 v[60:63], v[132:135], v[164:167], v[60:63]
	v_mfma_f32_16x16x32_bf16 v[56:59], v[140:143], v[164:167], v[56:59]
	v_mfma_f32_16x16x32_bf16 v[48:51], v[132:135], v[172:175], v[48:51]
	v_mfma_f32_16x16x32_bf16 v[40:43], v[140:143], v[172:175], v[40:43]
	v_mfma_f32_16x16x32_bf16 v[32:35], v[132:135], v[180:183], v[32:35]
	v_mfma_f32_16x16x32_bf16 v[24:27], v[140:143], v[180:183], v[24:27]
	v_mfma_f32_16x16x32_bf16 v[16:19], v[132:135], v[188:191], v[16:19]
	v_mfma_f32_16x16x32_bf16 v[8:11], v[140:143], v[188:191], v[8:11]
	v_mfma_f32_16x16x32_bf16 v[52:55], v[144:147], v[160:163], v[52:55]
	v_mfma_f32_16x16x32_bf16 v[44:47], v[152:155], v[160:163], v[44:47]
	v_mfma_f32_16x16x32_bf16 v[36:39], v[144:147], v[168:171], v[36:39]
	v_mfma_f32_16x16x32_bf16 v[28:31], v[152:155], v[168:171], v[28:31]
	v_mfma_f32_16x16x32_bf16 v[20:23], v[144:147], v[176:179], v[20:23]
	v_mfma_f32_16x16x32_bf16 v[12:15], v[152:155], v[176:179], v[12:15]
	v_mfma_f32_16x16x32_bf16 v[4:7], v[144:147], v[184:187], v[4:7]
	v_mfma_f32_16x16x32_bf16 v[0:3], v[152:155], v[184:187], v[0:3]
	v_mfma_f32_16x16x32_bf16 v[52:55], v[148:151], v[164:167], v[52:55]
	v_mfma_f32_16x16x32_bf16 v[44:47], v[156:159], v[164:167], v[44:47]
	v_mfma_f32_16x16x32_bf16 v[36:39], v[148:151], v[172:175], v[36:39]
	v_mfma_f32_16x16x32_bf16 v[28:31], v[156:159], v[172:175], v[28:31]
	v_mfma_f32_16x16x32_bf16 v[20:23], v[148:151], v[180:183], v[20:23]
	v_mfma_f32_16x16x32_bf16 v[12:15], v[156:159], v[180:183], v[12:15]
	v_mfma_f32_16x16x32_bf16 v[4:7], v[148:151], v[188:191], v[4:7]
	v_mfma_f32_16x16x32_bf16 v[0:3], v[156:159], v[188:191], v[0:3]
	s_barrier
	s_add_i32 s3, 0, 0x18000
	s_add_i32 s30, 0, 0x1c000
	ds_read_b128 v[128:131], v196
	ds_read_b128 v[132:135], v196 offset:1024
	ds_read_b128 v[136:139], v196 offset:2048
	ds_read_b128 v[140:143], v196 offset:3072
	ds_read_b128 v[144:147], v197
	ds_read_b128 v[148:151], v197 offset:1024
	ds_read_b128 v[152:155], v197 offset:2048
	ds_read_b128 v[156:159], v197 offset:3072
	s_add_u32 s66, s82, 0x130000
	s_addc_u32 s67, s83, 0
	s_mov_b32 m0, s64
	ds_read_b128 v[160:163], v223 offset:32768
	ds_read_b128 v[164:167], v223 offset:33792
	ds_read_b128 v[168:171], v223 offset:34816
	ds_read_b128 v[172:175], v223 offset:35840
	ds_read_b128 v[176:179], v223 offset:36864
	ds_read_b128 v[180:183], v223 offset:37888
	ds_read_b128 v[184:187], v223 offset:38912
	ds_read_b128 v[188:191], v223 offset:39936
	global_load_lds_dwordx4 v202, s[66:67]
	s_mov_b32 m0, s65
	s_nop 0
	global_load_lds_dwordx4 v200, s[66:67]
	s_waitcnt vmcnt(8)
	s_waitcnt lgkmcnt(0)
	s_barrier
; #define PG8_STAGE(bufoff, gbase, voff) do { _Pragma("unroll") for (int _i = 0; _i < 2; ++_i) \
;         __builtin_amdgcn_global_load_lds((const unsigned*)((const char*)(gbase) + (voff)[_i]), (PG8_LAS unsigned*)(lds + (bufoff) + ldsw + _i * 8192), 16, 0, 0); } while (0)
; #define PG8_LDA(dst, b, h) do { _Pragma("unroll") for (int m = 0; m < 4; ++m) _Pragma("unroll") for (int k = 0; k < 2; ++k) dst[m][k] = *(const PG8_LAS bf16x8*)(lds + PG8_SA(b, h) + aoff + m * 2048 + k * 1024); } while (0)
; #define PG8_MMA(ai, bj, At, Bt) do { __builtin_amdgcn_s_setprio(1); _Pragma("unroll") for (int m = 0; m < 4; ++m) _Pragma("unroll") for (int n = 0; n < 2; ++n) _Pragma("unroll") for (int k = 0; k < 2; ++k) \
;         acc[ai][bj][m][n] = __builtin_amdgcn_mfma_f32_16x16x32_bf16(Bt[n][k], At[m][k], acc[ai][bj][m][n], 0, 0, 0); __builtin_amdgcn_s_setprio(0); } while (0)
; #define PG8_WAIT_V(n) asm volatile("s_waitcnt vmcnt(" #n ")" ::: "memory")
; #define PG8_WAIT_L(n) asm volatile("s_waitcnt lgkmcnt(" #n ")" ::: "memory")
; #define PG8_BAR __builtin_amdgcn_s_barrier()
; #define PG8_SCHED __builtin_amdgcn_sched_barrier(0)
; template <class Epi, class Sched, bool ALIGN_EPI = false, bool SP2 = false>
; __device__ __forceinline__ void gemm_phase(PG8_LAS unsigned char* lds, const Gemm g, const Sched& S, const Epi& E) {
;     ...
;             PG8_WAIT_V(8); PG8_WAIT_L(0); PG8_BAR; PG8_MMA(0, 0, At, B0); PG8_MMA(0, 1, At, B1); PG8_BAR; PG8_SCHED;
;             PG8_LDA(At, 1, 1); PG8_STAGE(PG8_SB(1, 0), b3, voffB); PG8_STAGE(PG8_SB(1, 1), b3 + hstepB, voffB); PG8_STAGE(PG8_SA(1, 0), a3, voffA);
;             PG8_WAIT_V(8); PG8_WAIT_L(0); PG8_BAR; PG8_MMA(1, 0, At, B0); PG8_MMA(1, 1, At, B1); PG8_BAR; PG8_SCHED;
;     ...
;         if constexpr (ALIGN_EPI) { if (wr == 0) PG8_BAR; }
	s_waitcnt lgkmcnt(0)
	v_mfma_f32_16x16x32_bf16 v[124:127], v[128:131], v[160:163], v[124:127]
	v_mfma_f32_16x16x32_bf16 v[120:123], v[136:139], v[160:163], v[120:123]
	v_mfma_f32_16x16x32_bf16 v[112:115], v[128:131], v[168:171], v[112:115]
	v_mfma_f32_16x16x32_bf16 v[104:107], v[136:139], v[168:171], v[104:107]
	v_mfma_f32_16x16x32_bf16 v[96:99], v[128:131], v[176:179], v[96:99]
	v_mfma_f32_16x16x32_bf16 v[88:91], v[136:139], v[176:179], v[88:91]
	v_mfma_f32_16x16x32_bf16 v[80:83], v[128:131], v[184:187], v[80:83]
	v_mfma_f32_16x16x32_bf16 v[72:75], v[136:139], v[184:187], v[72:75]
	v_mfma_f32_16x16x32_bf16 v[124:127], v[132:135], v[164:167], v[124:127]
	v_mfma_f32_16x16x32_bf16 v[120:123], v[140:143], v[164:167], v[120:123]
	v_mfma_f32_16x16x32_bf16 v[112:115], v[132:135], v[172:175], v[112:115]
	v_mfma_f32_16x16x32_bf16 v[104:107], v[140:143], v[172:175], v[104:107]
	v_mfma_f32_16x16x32_bf16 v[96:99], v[132:135], v[180:183], v[96:99]
	v_mfma_f32_16x16x32_bf16 v[88:91], v[140:143], v[180:183], v[88:91]
	v_mfma_f32_16x16x32_bf16 v[80:83], v[132:135], v[188:191], v[80:83]
	v_mfma_f32_16x16x32_bf16 v[72:75], v[140:143], v[188:191], v[72:75]
	v_mfma_f32_16x16x32_bf16 v[116:119], v[144:147], v[160:163], v[116:119]
	v_mfma_f32_16x16x32_bf16 v[108:111], v[152:155], v[160:163], v[108:111]
	v_mfma_f32_16x16x32_bf16 v[100:103], v[144:147], v[168:171], v[100:103]
	v_mfma_f32_16x16x32_bf16 v[92:95], v[152:155], v[168:171], v[92:95]
	v_mfma_f32_16x16x32_bf16 v[84:87], v[144:147], v[176:179], v[84:87]
	v_mfma_f32_16x16x32_bf16 v[76:79], v[152:155], v[176:179], v[76:79]
	v_mfma_f32_16x16x32_bf16 v[68:71], v[144:147], v[184:187], v[68:71]
	v_mfma_f32_16x16x32_bf16 v[64:67], v[152:155], v[184:187], v[64:67]
	v_mfma_f32_16x16x32_bf16 v[116:119], v[148:151], v[164:167], v[116:119]
	v_mfma_f32_16x16x32_bf16 v[108:111], v[156:159], v[164:167], v[108:111]
	v_mfma_f32_16x16x32_bf16 v[100:103], v[148:151], v[172:175], v[100:103]
	v_mfma_f32_16x16x32_bf16 v[92:95], v[156:159], v[172:175], v[92:95]
	v_mfma_f32_16x16x32_bf16 v[84:87], v[148:151], v[180:183], v[84:87]
	v_mfma_f32_16x16x32_bf16 v[76:79], v[156:159], v[180:183], v[76:79]
	v_mfma_f32_16x16x32_bf16 v[68:71], v[148:151], v[188:191], v[68:71]
	v_mfma_f32_16x16x32_bf16 v[64:67], v[156:159], v[188:191], v[64:67]
	s_barrier
	s_add_i32 s3, s3, s49
	s_add_i32 m0, s3, 0xffffff80
	ds_read_b128 v[160:163], v223 offset:49152
	ds_read_b128 v[164:167], v223 offset:50176
	ds_read_b128 v[168:171], v223 offset:51200
	ds_read_b128 v[172:175], v223 offset:52224
	ds_read_b128 v[176:179], v223 offset:53248
	ds_read_b128 v[180:183], v223 offset:54272
	ds_read_b128 v[184:187], v223 offset:55296
	ds_read_b128 v[188:191], v223 offset:56320
	global_load_lds_dwordx4 v192, s[96:97] offset:128
	s_add_i32 m0, s3, 0x1f80
	s_add_i32 s3, s30, s49
	global_load_lds_dwordx4 v198, s[96:97] offset:128
	v_lshl_add_u64 v[208:209], v[212:213], 0, s[36:37]
	s_mov_b32 m0, s3
	s_nop 0
	global_load_lds_dwordx4 v[208:209], off
	v_lshl_add_u64 v[208:209], v[214:215], 0, s[36:37]
	s_add_i32 m0, s3, 0x2000
	s_nop 0
	global_load_lds_dwordx4 v[208:209], off
	s_add_i32 m0, s86, 0xffffff80
	s_nop 0
	global_load_lds_dwordx4 v202, s[82:83] offset:128
	s_add_i32 m0, s87, 0xffffff80
	s_nop 0
	global_load_lds_dwordx4 v200, s[82:83] offset:128
	s_waitcnt vmcnt(8)
	s_waitcnt lgkmcnt(0)
	s_barrier
	s_waitcnt lgkmcnt(0)
	v_mfma_f32_16x16x32_bf16 v[60:63], v[128:131], v[160:163], v[60:63]
	v_mfma_f32_16x16x32_bf16 v[56:59], v[136:139], v[160:163], v[56:59]
	v_mfma_f32_16x16x32_bf16 v[48:51], v[128:131], v[168:171], v[48:51]
	v_mfma_f32_16x16x32_bf16 v[40:43], v[136:139], v[168:171], v[40:43]
	v_mfma_f32_16x16x32_bf16 v[32:35], v[128:131], v[176:179], v[32:35]
	v_mfma_f32_16x16x32_bf16 v[24:27], v[136:139], v[176:179], v[24:27]
	v_mfma_f32_16x16x32_bf16 v[16:19], v[128:131], v[184:187], v[16:19]
	v_mfma_f32_16x16x32_bf16 v[8:11], v[136:139], v[184:187], v[8:11]
	v_mfma_f32_16x16x32_bf16 v[60:63], v[132:135], v[164:167], v[60:63]
	v_mfma_f32_16x16x32_bf16 v[56:59], v[140:143], v[164:167], v[56:59]
	v_mfma_f32_16x16x32_bf16 v[48:51], v[132:135], v[172:175], v[48:51]
	v_mfma_f32_16x16x32_bf16 v[40:43], v[140:143], v[172:175], v[40:43]
	v_mfma_f32_16x16x32_bf16 v[32:35], v[132:135], v[180:183], v[32:35]
	v_mfma_f32_16x16x32_bf16 v[24:27], v[140:143], v[180:183], v[24:27]
	v_mfma_f32_16x16x32_bf16 v[16:19], v[132:135], v[188:191], v[16:19]
	v_mfma_f32_16x16x32_bf16 v[8:11], v[140:143], v[188:191], v[8:11]
	v_mfma_f32_16x16x32_bf16 v[52:55], v[144:147], v[160:163], v[52:55]
	v_mfma_f32_16x16x32_bf16 v[44:47], v[152:155], v[160:163], v[44:47]
	v_mfma_f32_16x16x32_bf16 v[36:39], v[144:147], v[168:171], v[36:39]
	v_mfma_f32_16x16x32_bf16 v[28:31], v[152:155], v[168:171], v[28:31]
	v_mfma_f32_16x16x32_bf16 v[20:23], v[144:147], v[176:179], v[20:23]
	v_mfma_f32_16x16x32_bf16 v[12:15], v[152:155], v[176:179], v[12:15]
	v_mfma_f32_16x16x32_bf16 v[4:7], v[144:147], v[184:187], v[4:7]
	v_mfma_f32_16x16x32_bf16 v[0:3], v[152:155], v[184:187], v[0:3]
	v_mfma_f32_16x16x32_bf16 v[52:55], v[148:151], v[164:167], v[52:55]
	v_mfma_f32_16x16x32_bf16 v[44:47], v[156:159], v[164:167], v[44:47]
	v_mfma_f32_16x16x32_bf16 v[36:39], v[148:151], v[172:175], v[36:39]
	v_mfma_f32_16x16x32_bf16 v[28:31], v[156:159], v[172:175], v[28:31]
	v_mfma_f32_16x16x32_bf16 v[20:23], v[148:151], v[180:183], v[20:23]
	v_mfma_f32_16x16x32_bf16 v[12:15], v[156:159], v[180:183], v[12:15]
	v_mfma_f32_16x16x32_bf16 v[4:7], v[148:151], v[188:191], v[4:7]
	v_mfma_f32_16x16x32_bf16 v[0:3], v[156:159], v[188:191], v[0:3]
	s_barrier
	s_add_u32 s93, s93, 0x100
	s_addc_u32 s94, s94, 0
	s_cmp_ge_u32 s2, s80
	s_mov_b64 s[66:67], s[4:5]
	s_mov_b32 s82, s2
	s_cbranch_scc0 .LBB0_766
	s_and_b64 vcc, exec, s[12:13]
	s_cbranch_vccz .LBB0_769
	s_barrier

; #define PG8_STAGE(bufoff, gbase, voff) do { _Pragma("unroll") for (int _i = 0; _i < 2; ++_i) \
;         __builtin_amdgcn_global_load_lds((const unsigned*)((const char*)(gbase) + (voff)[_i]), (PG8_LAS unsigned*)(lds + (bufoff) + ldsw + _i * 8192), 16, 0, 0); } while (0)
; #define PG8_LDA(dst, b, h) do { _Pragma("unroll") for (int m = 0; m < 4; ++m) _Pragma("unroll") for (int k = 0; k < 2; ++k) dst[m][k] = *(const PG8_LAS bf16x8*)(lds + PG8_SA(b, h) + aoff + m * 2048 + k * 1024); } while (0)
; #define PG8_LDB(dst, b, h) do { _Pragma("unroll") for (int n = 0; n < 2; ++n) _Pragma("unroll") for (int k = 0; k < 2; ++k) dst[n][k] = *(const PG8_LAS bf16x8*)(lds + PG8_SB(b, h) + boff + n * 2048 + k * 1024); } while (0)
; #define PG8_SCHED __builtin_amdgcn_sched_barrier(0)
; template <class Epi, class Sched, bool ALIGN_EPI = false, bool SP2 = false>
; __device__ __forceinline__ void gemm_phase(PG8_LAS unsigned char* lds, const Gemm g, const Sched& S, const Epi& E) {
;     ...
;         const bool has_next = S.next(ui + 1, nxt);
;         const char* nA = has_next ? (const char*)g.A + (size_t)nxt.pm * tstepA : cA; const char* nB = has_next ? (const char*)g.Bt + (size_t)nxt.pn * tstepB : cB;
;         for (int t = 0; t < nt; t += 2) {
;             const bool last = (t == nt - 2);
;             const char* a1 = cA + (size_t)(t + 1) * kstep;
;             const char* a2 = last ? nA : cA + (size_t)(t + 2) * kstep; const char* b2 = last ? nB : cB + (size_t)(t + 2) * kstep;
;             const char* a3 = a2 + kstep; const char* b3 = b2 + kstep;
;             if (last && has_next) S.a_ready(nxt);
;             if constexpr (SP2) {
;             PG8_LDB(B0, 0, 0); PG8_LDB(B1, 0, 1); PG8_SCHED; PG8_LDA(At, 0, 0); PG8_STAGE(PG8_SA(1, 1), a1 + hstepA, voffA);
;     ...
; #pragma unroll
;         for (int a = 0; a < 2; ++a)
; #pragma unroll
;             for (int b = 0; b < 2; ++b)
; #pragma unroll
;                 for (int m = 0; m < 4; ++m)
; #pragma unroll
;                     for (int n = 0; n < 2; ++n) acc[a][b][m][n] = (f32x4){0.f, 0.f, 0.f, 0.f};
.LBB0_816:
	s_ashr_i32 s91, s90, 31
	s_lshl_b64 s[2:3], s[90:91], 19
	s_add_u32 s82, s24, s2
	s_addc_u32 s83, s25, s3
	s_and_b64 s[2:3], s[4:5], exec
	s_cselect_b32 s7, s83, s9
	s_cselect_b32 s12, s82, s8
	s_ashr_i32 s89, s88, 31
	s_lshl_b64 s[2:3], s[88:89], 19
	s_add_u32 s92, s34, s2
	s_addc_u32 s93, s80, s3
	s_and_b64 s[2:3], s[4:5], exec
	s_cselect_b32 s13, s93, s1
	s_cselect_b32 s15, s92, s0
	s_add_u32 s16, s0, 0x100
	s_addc_u32 s17, s1, 0
	s_add_u32 s0, s8, 0x40080
	v_mov_b32_e32 v0, 0
	s_addc_u32 s1, s9, 0
	s_mov_b32 s78, -2
	v_mov_b32_e32 v1, v0
	v_mov_b32_e32 v2, v0
	v_mov_b32_e32 v3, v0
	v_mov_b32_e32 v4, v0
	v_mov_b32_e32 v5, v0
	v_mov_b32_e32 v6, v0
	v_mov_b32_e32 v7, v0
	v_mov_b32_e32 v16, v0
	v_mov_b32_e32 v17, v0
	v_mov_b32_e32 v18, v0
	v_mov_b32_e32 v19, v0
	v_mov_b32_e32 v20, v0
	v_mov_b32_e32 v21, v0
	v_mov_b32_e32 v22, v0
	v_mov_b32_e32 v23, v0
	v_mov_b32_e32 v32, v0
	v_mov_b32_e32 v33, v0
	v_mov_b32_e32 v34, v0
	v_mov_b32_e32 v35, v0
	v_mov_b32_e32 v36, v0
	v_mov_b32_e32 v37, v0
	v_mov_b32_e32 v38, v0
	v_mov_b32_e32 v39, v0
	v_mov_b32_e32 v48, v0
	v_mov_b32_e32 v49, v0
	v_mov_b32_e32 v50, v0
	v_mov_b32_e32 v51, v0
	v_mov_b32_e32 v52, v0
	v_mov_b32_e32 v53, v0
	v_mov_b32_e32 v54, v0
	v_mov_b32_e32 v55, v0
	v_mov_b32_e32 v8, v0
	v_mov_b32_e32 v9, v0
	v_mov_b32_e32 v10, v0
	v_mov_b32_e32 v11, v0
	v_mov_b32_e32 v12, v0
	v_mov_b32_e32 v13, v0
	v_mov_b32_e32 v14, v0
	v_mov_b32_e32 v15, v0
	v_mov_b32_e32 v24, v0
	v_mov_b32_e32 v25, v0
	v_mov_b32_e32 v26, v0
	v_mov_b32_e32 v27, v0
	v_mov_b32_e32 v28, v0
	v_mov_b32_e32 v29, v0
	v_mov_b32_e32 v30, v0
	v_mov_b32_e32 v31, v0
	v_mov_b32_e32 v40, v0
	v_mov_b32_e32 v41, v0
	v_mov_b32_e32 v42, v0
	v_mov_b32_e32 v43, v0
	v_mov_b32_e32 v44, v0
	v_mov_b32_e32 v45, v0
	v_mov_b32_e32 v46, v0
	v_mov_b32_e32 v47, v0
	v_mov_b32_e32 v56, v0
	v_mov_b32_e32 v57, v0
	v_mov_b32_e32 v58, v0
	v_mov_b32_e32 v59, v0
	v_mov_b32_e32 v60, v0
	v_mov_b32_e32 v61, v0
	v_mov_b32_e32 v62, v0
	v_mov_b32_e32 v63, v0
	s_waitcnt vmcnt(0)
	v_mov_b32_e32 v64, v0
	v_mov_b32_e32 v65, v0
	v_mov_b32_e32 v66, v0
	v_mov_b32_e32 v67, v0
	v_mov_b32_e32 v68, v0
	v_mov_b32_e32 v69, v0
	v_mov_b32_e32 v70, v0
	v_mov_b32_e32 v71, v0
	v_mov_b32_e32 v96, v0
	v_mov_b32_e32 v97, v0
	v_mov_b32_e32 v98, v0
	v_mov_b32_e32 v99, v0
	v_mov_b32_e32 v100, v0
	v_mov_b32_e32 v101, v0
	v_mov_b32_e32 v102, v0
	v_mov_b32_e32 v103, v0
	v_mov_b32_e32 v128, v0
	v_mov_b32_e32 v129, v0
	v_mov_b32_e32 v130, v0
	v_mov_b32_e32 v131, v0
	v_mov_b32_e32 v132, v0
	v_mov_b32_e32 v133, v0
	v_mov_b32_e32 v134, v0
	v_mov_b32_e32 v135, v0
	v_mov_b32_e32 v160, v0
	v_mov_b32_e32 v161, v0
	v_mov_b32_e32 v162, v0
	v_mov_b32_e32 v163, v0
	v_mov_b32_e32 v164, v0
	v_mov_b32_e32 v165, v0
	v_mov_b32_e32 v166, v0
	v_mov_b32_e32 v167, v0
	v_mov_b32_e32 v88, v0
	v_mov_b32_e32 v89, v0
	v_mov_b32_e32 v90, v0
	v_mov_b32_e32 v91, v0
	v_mov_b32_e32 v92, v0
	v_mov_b32_e32 v93, v0
	v_mov_b32_e32 v94, v0
	v_mov_b32_e32 v95, v0
	v_mov_b32_e32 v120, v0
	v_mov_b32_e32 v121, v0
	v_mov_b32_e32 v122, v0
	v_mov_b32_e32 v123, v0
	v_mov_b32_e32 v124, v0
	v_mov_b32_e32 v125, v0
	v_mov_b32_e32 v126, v0
	v_mov_b32_e32 v127, v0
	v_mov_b32_e32 v152, v0
	v_mov_b32_e32 v153, v0
	v_mov_b32_e32 v154, v0
	v_mov_b32_e32 v155, v0
	v_mov_b32_e32 v156, v0
	v_mov_b32_e32 v157, v0
	v_mov_b32_e32 v158, v0
	v_mov_b32_e32 v159, v0
	v_mov_b32_e32 v184, v0
	v_mov_b32_e32 v185, v0
	v_mov_b32_e32 v186, v0
	v_mov_b32_e32 v187, v0
	v_mov_b32_e32 v188, v0
	v_mov_b32_e32 v189, v0
	v_mov_b32_e32 v190, v0
	v_mov_b32_e32 v191, v0
	v_add_u32_e32 v194, 0x10000, v240
	v_add_u32_e32 v195, 0x14000, v240
	v_add_u32_e32 v196, 0x18000, v240
	v_add_u32_e32 v197, 0x1c000, v240
.LBB0_817:
	s_add_u32 s2, s0, 0xfffc0080
	s_addc_u32 s3, s1, -1
	s_add_i32 s30, 0, 0x10000
	s_cmp_eq_u32 s78, 12
	s_cselect_b32 s11, s7, s3
	s_cselect_b32 s10, s12, s2
	s_cselect_b32 s9, s13, s17
	s_cselect_b32 s8, s15, s16
	s_add_i32 s31, 0, 0x14000
	ds_read_b128 v[72:75], v194
	ds_read_b128 v[76:79], v194 offset:1024
	ds_read_b128 v[80:83], v194 offset:2048
	ds_read_b128 v[84:87], v194 offset:3072
	ds_read_b128 v[104:107], v195
	ds_read_b128 v[108:111], v195 offset:1024
	ds_read_b128 v[112:115], v195 offset:2048
	ds_read_b128 v[116:119], v195 offset:3072
	s_add_i32 m0, s19, 0xc000
	ds_read_b128 v[136:139], v241
	ds_read_b128 v[140:143], v241 offset:1024
	ds_read_b128 v[144:147], v241 offset:2048
	ds_read_b128 v[148:151], v241 offset:3072
	ds_read_b128 v[168:171], v241 offset:4096
	ds_read_b128 v[172:175], v241 offset:5120
	ds_read_b128 v[176:179], v241 offset:6144
	ds_read_b128 v[180:183], v241 offset:7168
	global_load_lds_dwordx4 v206, s[0:1]
	s_add_i32 m0, s19, 0xe000
	s_nop 0
	global_load_lds_dwordx4 v204, s[0:1]
	s_waitcnt vmcnt(8)
	s_waitcnt lgkmcnt(0)
	s_barrier
; #define PG8_STAGE(bufoff, gbase, voff) do { _Pragma("unroll") for (int _i = 0; _i < 2; ++_i) \
;         __builtin_amdgcn_global_load_lds((const unsigned*)((const char*)(gbase) + (voff)[_i]), (PG8_LAS unsigned*)(lds + (bufoff) + ldsw + _i * 8192), 16, 0, 0); } while (0)
; #define PG8_LDA(dst, b, h) do { _Pragma("unroll") for (int m = 0; m < 4; ++m) _Pragma("unroll") for (int k = 0; k < 2; ++k) dst[m][k] = *(const PG8_LAS bf16x8*)(lds + PG8_SA(b, h) + aoff + m * 2048 + k * 1024); } while (0)
; #define PG8_MMA(ai, bj, At, Bt) do { __builtin_amdgcn_s_setprio(1); _Pragma("unroll") for (int m = 0; m < 4; ++m) _Pragma("unroll") for (int n = 0; n < 2; ++n) _Pragma("unroll") for (int k = 0; k < 2; ++k) \
;         acc[ai][bj][m][n] = __builtin_amdgcn_mfma_f32_16x16x32_bf16(Bt[n][k], At[m][k], acc[ai][bj][m][n], 0, 0, 0); __builtin_amdgcn_s_setprio(0); } while (0)
; #define PG8_WAIT_V(n) asm volatile("s_waitcnt vmcnt(" #n ")" ::: "memory")
; #define PG8_WAIT_L(n) asm volatile("s_waitcnt lgkmcnt(" #n ")" ::: "memory")
; #define PG8_BAR __builtin_amdgcn_s_barrier()
; #define PG8_SCHED __builtin_amdgcn_sched_barrier(0)
; template <class Epi, class Sched, bool ALIGN_EPI = false, bool SP2 = false>
; __device__ __forceinline__ void gemm_phase(PG8_LAS unsigned char* lds, const Gemm g, const Sched& S, const Epi& E) {
;     ...
;             PG8_WAIT_V(8); PG8_WAIT_L(0); PG8_BAR; PG8_MMA(0, 0, At, B0); PG8_MMA(0, 1, At, B1); PG8_BAR; PG8_SCHED;
;             PG8_LDA(At, 0, 1); PG8_STAGE(PG8_SB(0, 0), b2, voffB); PG8_STAGE(PG8_SB(0, 1), b2 + hstepB, voffB); PG8_STAGE(PG8_SA(0, 0), a2, voffA);
;             PG8_WAIT_V(8); PG8_WAIT_L(0); PG8_BAR; PG8_MMA(1, 0, At, B0); PG8_MMA(1, 1, At, B1); PG8_BAR; PG8_SCHED;
	s_waitcnt lgkmcnt(0)
	v_mfma_f32_16x16x32_bf16 v[188:191], v[72:75], v[136:139], v[188:191]
	v_mfma_f32_16x16x32_bf16 v[184:187], v[80:83], v[136:139], v[184:187]
	v_mfma_f32_16x16x32_bf16 v[156:159], v[72:75], v[144:147], v[156:159]
	v_mfma_f32_16x16x32_bf16 v[152:155], v[80:83], v[144:147], v[152:155]
	v_mfma_f32_16x16x32_bf16 v[124:127], v[72:75], v[168:171], v[124:127]
	v_mfma_f32_16x16x32_bf16 v[120:123], v[80:83], v[168:171], v[120:123]
	v_mfma_f32_16x16x32_bf16 v[92:95], v[72:75], v[176:179], v[92:95]
	v_mfma_f32_16x16x32_bf16 v[88:91], v[80:83], v[176:179], v[88:91]
	v_mfma_f32_16x16x32_bf16 v[188:191], v[76:79], v[140:143], v[188:191]
	v_mfma_f32_16x16x32_bf16 v[184:187], v[84:87], v[140:143], v[184:187]
	v_mfma_f32_16x16x32_bf16 v[156:159], v[76:79], v[148:151], v[156:159]
	v_mfma_f32_16x16x32_bf16 v[152:155], v[84:87], v[148:151], v[152:155]
	v_mfma_f32_16x16x32_bf16 v[124:127], v[76:79], v[172:175], v[124:127]
	v_mfma_f32_16x16x32_bf16 v[120:123], v[84:87], v[172:175], v[120:123]
	v_mfma_f32_16x16x32_bf16 v[92:95], v[76:79], v[180:183], v[92:95]
	v_mfma_f32_16x16x32_bf16 v[88:91], v[84:87], v[180:183], v[88:91]
	v_mfma_f32_16x16x32_bf16 v[164:167], v[104:107], v[136:139], v[164:167]
	v_mfma_f32_16x16x32_bf16 v[132:135], v[104:107], v[144:147], v[132:135]
	v_mfma_f32_16x16x32_bf16 v[128:131], v[112:115], v[144:147], v[128:131]
	v_mfma_f32_16x16x32_bf16 v[100:103], v[104:107], v[168:171], v[100:103]
	v_mfma_f32_16x16x32_bf16 v[96:99], v[112:115], v[168:171], v[96:99]
	v_mfma_f32_16x16x32_bf16 v[68:71], v[104:107], v[176:179], v[68:71]
	v_mfma_f32_16x16x32_bf16 v[64:67], v[112:115], v[176:179], v[64:67]
	v_mfma_f32_16x16x32_bf16 v[164:167], v[108:111], v[140:143], v[164:167]
	v_mfma_f32_16x16x32_bf16 v[136:139], v[112:115], v[136:139], v[160:163]
	v_mfma_f32_16x16x32_bf16 v[132:135], v[108:111], v[148:151], v[132:135]
	v_mfma_f32_16x16x32_bf16 v[128:131], v[116:119], v[148:151], v[128:131]
	v_mfma_f32_16x16x32_bf16 v[100:103], v[108:111], v[172:175], v[100:103]
	v_mfma_f32_16x16x32_bf16 v[96:99], v[116:119], v[172:175], v[96:99]
	v_mfma_f32_16x16x32_bf16 v[68:71], v[108:111], v[180:183], v[68:71]
	v_mfma_f32_16x16x32_bf16 v[64:67], v[116:119], v[180:183], v[64:67]
	v_mfma_f32_16x16x32_bf16 v[136:139], v[116:119], v[140:143], v[136:139]
	s_barrier
	s_add_i32 s2, s30, s18
	s_mov_b32 m0, s2
	ds_read_b128 v[140:143], v241 offset:16384
	ds_read_b128 v[144:147], v241 offset:17408
	ds_read_b128 v[148:151], v241 offset:18432
	ds_read_b128 v[160:163], v241 offset:19456
	ds_read_b128 v[168:171], v241 offset:20480
	ds_read_b128 v[172:175], v241 offset:21504
	ds_read_b128 v[176:179], v241 offset:22528
	ds_read_b128 v[180:183], v241 offset:23552
	global_load_lds_dwordx4 v192, s[8:9]
	s_add_i32 m0, s2, 0x2000
	s_add_u32 s2, s8, 0x40000
	s_addc_u32 s3, s9, 0
	s_add_i32 s30, s31, s18
	global_load_lds_dwordx4 v202, s[8:9]
	s_mov_b32 m0, s30
	s_nop 0
	global_load_lds_dwordx4 v192, s[2:3]
	s_add_i32 m0, s30, 0x2000
	s_nop 0
	global_load_lds_dwordx4 v202, s[2:3]
	s_mov_b32 m0, s19
	s_nop 0
	global_load_lds_dwordx4 v198, s[10:11]
	s_mov_b32 m0, s45
	s_nop 0
	global_load_lds_dwordx4 v200, s[10:11]
	s_waitcnt vmcnt(8)
	s_waitcnt lgkmcnt(0)
	s_barrier
	s_waitcnt lgkmcnt(0)
	v_mfma_f32_16x16x32_bf16 v[60:63], v[72:75], v[140:143], v[60:63]
	v_mfma_f32_16x16x32_bf16 v[56:59], v[80:83], v[140:143], v[56:59]
	v_mfma_f32_16x16x32_bf16 v[44:47], v[72:75], v[148:151], v[44:47]
	v_mfma_f32_16x16x32_bf16 v[40:43], v[80:83], v[148:151], v[40:43]
	v_mfma_f32_16x16x32_bf16 v[28:31], v[72:75], v[168:171], v[28:31]
	v_mfma_f32_16x16x32_bf16 v[24:27], v[80:83], v[168:171], v[24:27]
	v_mfma_f32_16x16x32_bf16 v[12:15], v[72:75], v[176:179], v[12:15]
	v_mfma_f32_16x16x32_bf16 v[8:11], v[80:83], v[176:179], v[8:11]
	v_mfma_f32_16x16x32_bf16 v[60:63], v[76:79], v[144:147], v[60:63]
	v_mfma_f32_16x16x32_bf16 v[56:59], v[84:87], v[144:147], v[56:59]
	v_mfma_f32_16x16x32_bf16 v[44:47], v[76:79], v[160:163], v[44:47]
	v_mfma_f32_16x16x32_bf16 v[40:43], v[84:87], v[160:163], v[40:43]
	v_mfma_f32_16x16x32_bf16 v[28:31], v[76:79], v[172:175], v[28:31]
	v_mfma_f32_16x16x32_bf16 v[24:27], v[84:87], v[172:175], v[24:27]
	v_mfma_f32_16x16x32_bf16 v[12:15], v[76:79], v[180:183], v[12:15]
	v_mfma_f32_16x16x32_bf16 v[8:11], v[84:87], v[180:183], v[8:11]
	v_mfma_f32_16x16x32_bf16 v[52:55], v[104:107], v[140:143], v[52:55]
	v_mfma_f32_16x16x32_bf16 v[48:51], v[112:115], v[140:143], v[48:51]
	v_mfma_f32_16x16x32_bf16 v[36:39], v[104:107], v[148:151], v[36:39]
	v_mfma_f32_16x16x32_bf16 v[32:35], v[112:115], v[148:151], v[32:35]
	v_mfma_f32_16x16x32_bf16 v[20:23], v[104:107], v[168:171], v[20:23]
	v_mfma_f32_16x16x32_bf16 v[16:19], v[112:115], v[168:171], v[16:19]
	v_mfma_f32_16x16x32_bf16 v[4:7], v[104:107], v[176:179], v[4:7]
	v_mfma_f32_16x16x32_bf16 v[0:3], v[112:115], v[176:179], v[0:3]
	v_mfma_f32_16x16x32_bf16 v[52:55], v[108:111], v[144:147], v[52:55]
	v_mfma_f32_16x16x32_bf16 v[48:51], v[116:119], v[144:147], v[48:51]
	v_mfma_f32_16x16x32_bf16 v[36:39], v[108:111], v[160:163], v[36:39]
	v_mfma_f32_16x16x32_bf16 v[32:35], v[116:119], v[160:163], v[32:35]
	v_mfma_f32_16x16x32_bf16 v[20:23], v[108:111], v[172:175], v[20:23]
	v_mfma_f32_16x16x32_bf16 v[16:19], v[116:119], v[172:175], v[16:19]
	v_mfma_f32_16x16x32_bf16 v[4:7], v[108:111], v[180:183], v[4:7]
	v_mfma_f32_16x16x32_bf16 v[0:3], v[116:119], v[180:183], v[0:3]
	s_barrier
; #define PG8_STAGE(bufoff, gbase, voff) do { _Pragma("unroll") for (int _i = 0; _i < 2; ++_i) \
;         __builtin_amdgcn_global_load_lds((const unsigned*)((const char*)(gbase) + (voff)[_i]), (PG8_LAS unsigned*)(lds + (bufoff) + ldsw + _i * 8192), 16, 0, 0); } while (0)
; #define PG8_LDA(dst, b, h) do { _Pragma("unroll") for (int m = 0; m < 4; ++m) _Pragma("unroll") for (int k = 0; k < 2; ++k) dst[m][k] = *(const PG8_LAS bf16x8*)(lds + PG8_SA(b, h) + aoff + m * 2048 + k * 1024); } while (0)
; #define PG8_LDB(dst, b, h) do { _Pragma("unroll") for (int n = 0; n < 2; ++n) _Pragma("unroll") for (int k = 0; k < 2; ++k) dst[n][k] = *(const PG8_LAS bf16x8*)(lds + PG8_SB(b, h) + boff + n * 2048 + k * 1024); } while (0)
; #define PG8_MMA(ai, bj, At, Bt) do { __builtin_amdgcn_s_setprio(1); _Pragma("unroll") for (int m = 0; m < 4; ++m) _Pragma("unroll") for (int n = 0; n < 2; ++n) _Pragma("unroll") for (int k = 0; k < 2; ++k) \
;         acc[ai][bj][m][n] = __builtin_amdgcn_mfma_f32_16x16x32_bf16(Bt[n][k], At[m][k], acc[ai][bj][m][n], 0, 0, 0); __builtin_amdgcn_s_setprio(0); } while (0)
; #define PG8_WAIT_V(n) asm volatile("s_waitcnt vmcnt(" #n ")" ::: "memory")
; #define PG8_WAIT_L(n) asm volatile("s_waitcnt lgkmcnt(" #n ")" ::: "memory")
; #define PG8_BAR __builtin_amdgcn_s_barrier()
; #define PG8_SCHED __builtin_amdgcn_sched_barrier(0)
; template <class Epi, class Sched, bool ALIGN_EPI = false, bool SP2 = false>
; __device__ __forceinline__ void gemm_phase(PG8_LAS unsigned char* lds, const Gemm g, const Sched& S, const Epi& E) {
;     ...
;             PG8_LDB(B0, 1, 0); PG8_LDB(B1, 1, 1); PG8_SCHED; PG8_LDA(At, 1, 0); PG8_STAGE(PG8_SA(0, 1), a2 + hstepA, voffA);
;             PG8_WAIT_V(8); PG8_WAIT_L(0); PG8_BAR; PG8_MMA(0, 0, At, B0); PG8_MMA(0, 1, At, B1); PG8_BAR; PG8_SCHED;
;             PG8_LDA(At, 1, 1); PG8_STAGE(PG8_SB(1, 0), b3, voffB); PG8_STAGE(PG8_SB(1, 1), b3 + hstepB, voffB); PG8_STAGE(PG8_SA(1, 0), a3, voffA);
;             PG8_WAIT_V(8); PG8_WAIT_L(0); PG8_BAR; PG8_MMA(1, 0, At, B0); PG8_MMA(1, 1, At, B1); PG8_BAR; PG8_SCHED;
	s_add_i32 s30, 0, 0x18000
	s_add_i32 s31, 0, 0x1c000
	ds_read_b128 v[72:75], v196
	ds_read_b128 v[76:79], v196 offset:1024
	ds_read_b128 v[80:83], v196 offset:2048
	ds_read_b128 v[84:87], v196 offset:3072
	ds_read_b128 v[104:107], v197
	ds_read_b128 v[108:111], v197 offset:1024
	ds_read_b128 v[112:115], v197 offset:2048
	ds_read_b128 v[116:119], v197 offset:3072
	s_add_u32 s2, s10, 0x40000
	s_addc_u32 s3, s11, 0
	s_mov_b32 m0, s64
	ds_read_b128 v[140:143], v241 offset:32768
	ds_read_b128 v[144:147], v241 offset:33792
	ds_read_b128 v[148:151], v241 offset:34816
	ds_read_b128 v[168:171], v241 offset:35840
	ds_read_b128 v[172:175], v241 offset:36864
	ds_read_b128 v[176:179], v241 offset:37888
	ds_read_b128 v[180:183], v241 offset:38912
	ds_read_b128 v[208:211], v241 offset:39936
	global_load_lds_dwordx4 v198, s[2:3]
	s_mov_b32 m0, s65
	s_nop 0
	global_load_lds_dwordx4 v200, s[2:3]
	s_waitcnt vmcnt(8)
	s_waitcnt lgkmcnt(0)
	s_barrier
	s_waitcnt lgkmcnt(0)
	v_mfma_f32_16x16x32_bf16 v[160:163], v[72:75], v[140:143], v[188:191]
	v_mfma_f32_16x16x32_bf16 v[188:191], v[76:79], v[144:147], v[160:163]
	v_mfma_f32_16x16x32_bf16 v[160:163], v[80:83], v[140:143], v[184:187]
	v_mfma_f32_16x16x32_bf16 v[156:159], v[72:75], v[148:151], v[156:159]
	v_mfma_f32_16x16x32_bf16 v[152:155], v[80:83], v[148:151], v[152:155]
	v_mfma_f32_16x16x32_bf16 v[124:127], v[72:75], v[172:175], v[124:127]
	v_mfma_f32_16x16x32_bf16 v[120:123], v[80:83], v[172:175], v[120:123]
	v_mfma_f32_16x16x32_bf16 v[92:95], v[72:75], v[180:183], v[92:95]
	v_mfma_f32_16x16x32_bf16 v[88:91], v[80:83], v[180:183], v[88:91]
	v_mfma_f32_16x16x32_bf16 v[184:187], v[84:87], v[144:147], v[160:163]
	v_mfma_f32_16x16x32_bf16 v[156:159], v[76:79], v[168:171], v[156:159]
	v_mfma_f32_16x16x32_bf16 v[152:155], v[84:87], v[168:171], v[152:155]
	v_mfma_f32_16x16x32_bf16 v[124:127], v[76:79], v[176:179], v[124:127]
	v_mfma_f32_16x16x32_bf16 v[120:123], v[84:87], v[176:179], v[120:123]
	v_mfma_f32_16x16x32_bf16 v[92:95], v[76:79], v[208:211], v[92:95]
	v_mfma_f32_16x16x32_bf16 v[88:91], v[84:87], v[208:211], v[88:91]
	v_mfma_f32_16x16x32_bf16 v[160:163], v[104:107], v[140:143], v[164:167]
	v_mfma_f32_16x16x32_bf16 v[136:139], v[112:115], v[140:143], v[136:139]
	v_mfma_f32_16x16x32_bf16 v[132:135], v[104:107], v[148:151], v[132:135]
	v_mfma_f32_16x16x32_bf16 v[128:131], v[112:115], v[148:151], v[128:131]
	v_mfma_f32_16x16x32_bf16 v[100:103], v[104:107], v[172:175], v[100:103]
	v_mfma_f32_16x16x32_bf16 v[96:99], v[112:115], v[172:175], v[96:99]
	v_mfma_f32_16x16x32_bf16 v[68:71], v[104:107], v[180:183], v[68:71]
	v_mfma_f32_16x16x32_bf16 v[64:67], v[112:115], v[180:183], v[64:67]
	v_mfma_f32_16x16x32_bf16 v[164:167], v[108:111], v[144:147], v[160:163]
	v_mfma_f32_16x16x32_bf16 v[160:163], v[116:119], v[144:147], v[136:139]
	v_mfma_f32_16x16x32_bf16 v[132:135], v[108:111], v[168:171], v[132:135]
	v_mfma_f32_16x16x32_bf16 v[128:131], v[116:119], v[168:171], v[128:131]
	v_mfma_f32_16x16x32_bf16 v[100:103], v[108:111], v[176:179], v[100:103]
	v_mfma_f32_16x16x32_bf16 v[96:99], v[116:119], v[176:179], v[96:99]
	v_mfma_f32_16x16x32_bf16 v[68:71], v[108:111], v[208:211], v[68:71]
	v_mfma_f32_16x16x32_bf16 v[64:67], v[116:119], v[208:211], v[64:67]
	s_barrier
	s_add_i32 s2, s30, s18
	s_add_i32 m0, s2, 0xffffff80
	ds_read_b128 v[136:139], v241 offset:49152
	ds_read_b128 v[140:143], v241 offset:50176
	ds_read_b128 v[144:147], v241 offset:51200
	ds_read_b128 v[148:151], v241 offset:52224
	ds_read_b128 v[168:171], v241 offset:53248
	ds_read_b128 v[172:175], v241 offset:54272
	ds_read_b128 v[176:179], v241 offset:55296
	ds_read_b128 v[180:183], v241 offset:56320
	global_load_lds_dwordx4 v192, s[8:9] offset:128
	s_add_i32 m0, s2, 0x1f80
	s_add_u32 s2, s8, 0x40080
	global_load_lds_dwordx4 v202, s[8:9] offset:128
	s_addc_u32 s3, s9, 0
	s_add_i32 s8, s31, s18
	s_mov_b32 m0, s8
	s_nop 0
	global_load_lds_dwordx4 v192, s[2:3]
	s_add_i32 m0, s8, 0x2000
	s_nop 0
	global_load_lds_dwordx4 v202, s[2:3]
	s_add_i32 m0, s21, 0xffffff80
	s_nop 0
	global_load_lds_dwordx4 v198, s[10:11] offset:128
	s_add_i32 m0, s62, 0xffffff80
	s_nop 0
	global_load_lds_dwordx4 v200, s[10:11] offset:128
	s_waitcnt vmcnt(8)
	s_waitcnt lgkmcnt(0)
	s_barrier
	s_waitcnt lgkmcnt(0)
	v_mfma_f32_16x16x32_bf16 v[60:63], v[72:75], v[136:139], v[60:63]
	v_mfma_f32_16x16x32_bf16 v[56:59], v[80:83], v[136:139], v[56:59]
	v_mfma_f32_16x16x32_bf16 v[44:47], v[72:75], v[144:147], v[44:47]
	v_mfma_f32_16x16x32_bf16 v[40:43], v[80:83], v[144:147], v[40:43]
	v_mfma_f32_16x16x32_bf16 v[28:31], v[72:75], v[168:171], v[28:31]
	v_mfma_f32_16x16x32_bf16 v[24:27], v[80:83], v[168:171], v[24:27]
	v_mfma_f32_16x16x32_bf16 v[12:15], v[72:75], v[176:179], v[12:15]
	v_mfma_f32_16x16x32_bf16 v[8:11], v[80:83], v[176:179], v[8:11]
	v_mfma_f32_16x16x32_bf16 v[60:63], v[76:79], v[140:143], v[60:63]
	v_mfma_f32_16x16x32_bf16 v[56:59], v[84:87], v[140:143], v[56:59]
	v_mfma_f32_16x16x32_bf16 v[44:47], v[76:79], v[148:151], v[44:47]
	v_mfma_f32_16x16x32_bf16 v[40:43], v[84:87], v[148:151], v[40:43]
	v_mfma_f32_16x16x32_bf16 v[28:31], v[76:79], v[172:175], v[28:31]
	v_mfma_f32_16x16x32_bf16 v[24:27], v[84:87], v[172:175], v[24:27]
	v_mfma_f32_16x16x32_bf16 v[12:15], v[76:79], v[180:183], v[12:15]
	v_mfma_f32_16x16x32_bf16 v[8:11], v[84:87], v[180:183], v[8:11]
	v_mfma_f32_16x16x32_bf16 v[52:55], v[104:107], v[136:139], v[52:55]
	v_mfma_f32_16x16x32_bf16 v[48:51], v[112:115], v[136:139], v[48:51]
	v_mfma_f32_16x16x32_bf16 v[36:39], v[104:107], v[144:147], v[36:39]
	v_mfma_f32_16x16x32_bf16 v[32:35], v[112:115], v[144:147], v[32:35]
	v_mfma_f32_16x16x32_bf16 v[20:23], v[104:107], v[168:171], v[20:23]
	v_mfma_f32_16x16x32_bf16 v[16:19], v[112:115], v[168:171], v[16:19]
	v_mfma_f32_16x16x32_bf16 v[4:7], v[104:107], v[176:179], v[4:7]
	v_mfma_f32_16x16x32_bf16 v[0:3], v[112:115], v[176:179], v[0:3]
	v_mfma_f32_16x16x32_bf16 v[52:55], v[108:111], v[140:143], v[52:55]
	v_mfma_f32_16x16x32_bf16 v[48:51], v[116:119], v[140:143], v[48:51]
	v_mfma_f32_16x16x32_bf16 v[36:39], v[108:111], v[148:151], v[36:39]
	v_mfma_f32_16x16x32_bf16 v[32:35], v[116:119], v[148:151], v[32:35]
	v_mfma_f32_16x16x32_bf16 v[20:23], v[108:111], v[172:175], v[20:23]
	v_mfma_f32_16x16x32_bf16 v[16:19], v[116:119], v[172:175], v[16:19]
	v_mfma_f32_16x16x32_bf16 v[4:7], v[108:111], v[180:183], v[4:7]
	v_mfma_f32_16x16x32_bf16 v[0:3], v[116:119], v[180:183], v[0:3]
	s_barrier
	s_add_i32 s78, s78, 2
	s_add_u32 s16, s16, 0x100
	s_addc_u32 s17, s17, 0
	s_add_u32 s0, s0, 0x100
	s_addc_u32 s1, s1, 0
	s_cmp_gt_u32 s78, 13
	s_cbranch_scc0 .LBB0_817
	s_and_b64 vcc, exec, s[66:67]
	s_cbranch_vccz .LBB0_820
	s_barrier
